# v11 + relu2 epilogue: drop identity canonicalize v_max (keeping store WAR wait states) + fused-LN row stats via v_permlane16/32_swap instead of serialized ds_bpermute
# speedup vs baseline: 1.0019x; 1.0019x over previous
.LBB0_656:
	s_lshl_b32 s26, s25, 8
	s_add_i32 s1, s26, s45
	s_lshl_b32 s0, s12, 5
	v_or_b32_e32 v130, s1, v146
	s_lshl_b32 s1, s84, 8
	v_lshrrev_b32_e32 v131, 1, v164
	s_or_b32 s0, s1, s0
	v_and_or_b32 v162, v131, 24, s0
	v_ashrrev_i32_e32 v163, 31, v162
	v_ashrrev_i32_e32 v131, 31, v130
	v_lshl_add_u64 v[132:133], v[162:163], 1, s[34:35]
	v_lshlrev_b64 v[134:135], 12, v[130:131]
	v_lshl_add_u64 v[146:147], v[132:133], 0, v[134:135]
	v_or_b32_e32 v134, 16, v130
	v_ashrrev_i32_e32 v135, 31, v134
	v_lshlrev_b64 v[134:135], 12, v[134:135]
	v_lshl_add_u64 v[134:135], v[132:133], 0, v[134:135]
	s_barrier
	global_load_dwordx4 v[148:151], v[146:147], off
	global_load_dwordx4 v[152:155], v[146:147], off offset:256
	global_load_dwordx4 v[156:159], v[134:135], off
	global_load_dwordx4 v[168:171], v[134:135], off offset:256
	v_or_b32_e32 v134, 32, v130
	v_or_b32_e32 v130, 48, v130
	v_ashrrev_i32_e32 v135, 31, v134
	v_ashrrev_i32_e32 v131, 31, v130
	v_lshlrev_b64 v[134:135], 12, v[134:135]
	v_lshlrev_b64 v[130:131], 12, v[130:131]
	v_lshl_add_u64 v[134:135], v[132:133], 0, v[134:135]
	v_lshl_add_u64 v[130:131], v[132:133], 0, v[130:131]
	global_load_dwordx4 v[142:145], v[134:135], off
	global_load_dwordx4 v[138:141], v[134:135], off offset:256
	s_nop 0
	global_load_dwordx4 v[134:137], v[130:131], off
	s_nop 0
	global_load_dwordx4 v[130:133], v[130:131], off offset:256
	s_mov_b32 s18, 0x3fd744fd
	s_mov_b64 s[0:1], 0x80000
	v_and_b32_e32 v167, 64, v219
	v_xor_b32_e32 v165, 16, v219
	v_add_u32_e32 v167, 64, v167
	v_and_b32_e32 v166, 63, v164
	s_waitcnt vmcnt(0)
	s_nop 0
	v_lshlrev_b32_e32 v160, 16, v148
	v_and_b32_e32 v161, 0xffff0000, v148
	v_lshlrev_b32_e32 v148, 16, v149
	v_and_b32_e32 v149, 0xffff0000, v149
	v_pk_fma_f32 v[92:93], v[148:149], s[18:19], v[92:93] op_sel_hi:[1,0,1]
	v_lshlrev_b32_e32 v148, 16, v150
	v_and_b32_e32 v149, 0xffff0000, v150
	v_pk_fma_f32 v[94:95], v[148:149], s[18:19], v[94:95] op_sel_hi:[1,0,1]
	v_lshlrev_b32_e32 v148, 16, v152
	v_and_b32_e32 v149, 0xffff0000, v152
	v_pk_fma_f32 v[10:11], v[148:149], s[18:19], v[10:11] op_sel_hi:[1,0,1]
	v_lshlrev_b32_e32 v148, 16, v154
	v_and_b32_e32 v149, 0xffff0000, v154
	v_pk_fma_f32 v[14:15], v[148:149], s[18:19], v[14:15] op_sel_hi:[1,0,1]
	v_lshlrev_b32_e32 v148, 16, v156
	v_and_b32_e32 v149, 0xffff0000, v156
	v_pk_fma_f32 v[102:103], v[148:149], s[18:19], v[102:103] op_sel_hi:[1,0,1]
	v_lshlrev_b32_e32 v148, 16, v158
	v_and_b32_e32 v149, 0xffff0000, v158
	v_pk_fma_f32 v[106:107], v[148:149], s[18:19], v[106:107] op_sel_hi:[1,0,1]
	v_lshlrev_b32_e32 v148, 16, v168
	v_and_b32_e32 v149, 0xffff0000, v168
	v_pk_fma_f32 v[26:27], v[148:149], s[18:19], v[26:27] op_sel_hi:[1,0,1]
	v_lshlrev_b32_e32 v148, 16, v170
	v_and_b32_e32 v149, 0xffff0000, v170
	v_pk_fma_f32 v[38:39], v[148:149], s[18:19], v[38:39] op_sel_hi:[1,0,1]
	v_lshlrev_b32_e32 v148, 16, v142
	v_and_b32_e32 v149, 0xffff0000, v142
	v_lshlrev_b32_e32 v142, 16, v143
	v_and_b32_e32 v143, 0xffff0000, v143
	v_pk_fma_f32 v[116:117], v[142:143], s[18:19], v[116:117] op_sel_hi:[1,0,1]
	v_lshlrev_b32_e32 v142, 16, v144
	v_and_b32_e32 v143, 0xffff0000, v144
	v_pk_fma_f32 v[118:119], v[142:143], s[18:19], v[118:119] op_sel_hi:[1,0,1]
	v_lshlrev_b32_e32 v142, 16, v138
	v_and_b32_e32 v143, 0xffff0000, v138
	v_lshlrev_b32_e32 v138, 16, v139
	v_and_b32_e32 v139, 0xffff0000, v139
	v_pk_fma_f32 v[60:61], v[138:139], s[18:19], v[60:61] op_sel_hi:[1,0,1]
	v_lshlrev_b32_e32 v138, 16, v140
	v_and_b32_e32 v139, 0xffff0000, v140
	v_lshlrev_b32_e32 v150, 16, v151
	v_and_b32_e32 v151, 0xffff0000, v151
	v_pk_fma_f32 v[62:63], v[138:139], s[18:19], v[62:63] op_sel_hi:[1,0,1]
	v_lshlrev_b32_e32 v138, 16, v134
	v_and_b32_e32 v139, 0xffff0000, v134
	v_lshlrev_b32_e32 v134, 16, v135
	v_and_b32_e32 v135, 0xffff0000, v135
	v_pk_fma_f32 v[96:97], v[150:151], s[18:19], v[96:97] op_sel_hi:[1,0,1]
	v_lshlrev_b32_e32 v150, 16, v153
	v_and_b32_e32 v151, 0xffff0000, v153
	v_pk_fma_f32 v[124:125], v[134:135], s[18:19], v[124:125] op_sel_hi:[1,0,1]
	v_lshlrev_b32_e32 v134, 16, v136
	v_and_b32_e32 v135, 0xffff0000, v136
	v_pk_fma_f32 v[12:13], v[150:151], s[18:19], v[12:13] op_sel_hi:[1,0,1]
	v_lshlrev_b32_e32 v150, 16, v155
	v_and_b32_e32 v151, 0xffff0000, v155
	v_pk_fma_f32 v[126:127], v[134:135], s[18:19], v[126:127] op_sel_hi:[1,0,1]
	v_lshlrev_b32_e32 v134, 16, v130
	v_and_b32_e32 v135, 0xffff0000, v130
	v_lshlrev_b32_e32 v130, 16, v131
	v_and_b32_e32 v131, 0xffff0000, v131
	v_pk_fma_f32 v[16:17], v[150:151], s[18:19], v[16:17] op_sel_hi:[1,0,1]
	v_lshlrev_b32_e32 v150, 16, v157
	v_and_b32_e32 v151, 0xffff0000, v157
	v_pk_fma_f32 v[76:77], v[130:131], s[18:19], v[76:77] op_sel_hi:[1,0,1]
	v_pk_fma_f32 v[74:75], v[134:135], s[18:19], v[74:75] op_sel_hi:[1,0,1]
	v_lshlrev_b32_e32 v130, 16, v132
	v_and_b32_e32 v131, 0xffff0000, v132
	v_lshl_add_u64 v[134:135], v[146:147], 0, s[0:1]
	s_mov_b32 s0, 0x80000
	v_pk_fma_f32 v[104:105], v[150:151], s[18:19], v[104:105] op_sel_hi:[1,0,1]
	v_lshlrev_b32_e32 v150, 16, v159
	v_and_b32_e32 v151, 0xffff0000, v159
	v_pk_fma_f32 v[78:79], v[130:131], s[18:19], v[78:79] op_sel_hi:[1,0,1]
	v_add_co_u32_e32 v130, vcc, s0, v146
	s_mov_b64 s[0:1], 0x90000
	v_pk_fma_f32 v[108:109], v[150:151], s[18:19], v[108:109] op_sel_hi:[1,0,1]
	v_lshlrev_b32_e32 v150, 16, v169
	v_and_b32_e32 v151, 0xffff0000, v169
	v_lshlrev_b32_e32 v140, 16, v141
	v_and_b32_e32 v141, 0xffff0000, v141
	v_pk_fma_f32 v[122:123], v[138:139], s[18:19], v[122:123] op_sel_hi:[1,0,1]
	v_addc_co_u32_e32 v131, vcc, 0, v147, vcc
	v_lshl_add_u64 v[138:139], v[146:147], 0, s[0:1]
	s_mov_b32 s0, 0x90000
	v_pk_fma_f32 v[28:29], v[150:151], s[18:19], v[28:29] op_sel_hi:[1,0,1]
	v_lshlrev_b32_e32 v150, 16, v171
	v_and_b32_e32 v151, 0xffff0000, v171
	v_lshlrev_b32_e32 v144, 16, v145
	v_and_b32_e32 v145, 0xffff0000, v145
	v_pk_fma_f32 v[64:65], v[140:141], s[18:19], v[64:65] op_sel_hi:[1,0,1]
	v_lshlrev_b32_e32 v136, 16, v137
	v_and_b32_e32 v137, 0xffff0000, v137
	v_lshlrev_b32_e32 v132, 16, v133
	v_and_b32_e32 v133, 0xffff0000, v133
	v_add_co_u32_e32 v140, vcc, s0, v146
	v_pk_fma_f32 v[90:91], v[160:161], s[18:19], v[90:91] op_sel_hi:[1,0,1]
	v_pk_fma_f32 v[40:41], v[150:151], s[18:19], v[40:41] op_sel_hi:[1,0,1]
	v_pk_fma_f32 v[114:115], v[148:149], s[18:19], v[114:115] op_sel_hi:[1,0,1]
	v_pk_fma_f32 v[120:121], v[144:145], s[18:19], v[120:121] op_sel_hi:[1,0,1]
	v_pk_fma_f32 v[58:59], v[142:143], s[18:19], v[58:59] op_sel_hi:[1,0,1]
	v_pk_fma_f32 v[128:129], v[136:137], s[18:19], v[128:129] op_sel_hi:[1,0,1]
	v_pk_fma_f32 v[80:81], v[132:133], s[18:19], v[80:81] op_sel_hi:[1,0,1]
	v_addc_co_u32_e32 v141, vcc, 0, v147, vcc
	s_mov_b64 s[0:1], 0xa0000
	global_load_dwordx4 v[130:133], v[130:131], off
	s_nop 0
	global_load_dwordx4 v[134:137], v[134:135], off offset:256
	s_nop 0
	global_load_dwordx4 v[150:153], v[140:141], off
	global_load_dwordx4 v[154:157], v[138:139], off offset:256
	v_lshl_add_u64 v[138:139], v[146:147], 0, s[0:1]
	s_mov_b32 s0, 0xa0000
	v_add_co_u32_e32 v140, vcc, s0, v146
	s_mov_b64 s[0:1], 0xb0000
	s_nop 0
	v_addc_co_u32_e32 v141, vcc, 0, v147, vcc
	global_load_dwordx4 v[158:161], v[140:141], off
	global_load_dwordx4 v[168:171], v[138:139], off offset:256
	v_lshl_add_u64 v[138:139], v[146:147], 0, s[0:1]
	s_mov_b32 s0, 0xb0000
	v_add_co_u32_e32 v140, vcc, s0, v146
	v_mov_b32_e32 v172, v94
	s_nop 0
	v_addc_co_u32_e32 v141, vcc, 0, v147, vcc
	global_load_dwordx4 v[140:143], v[140:141], off
	s_nop 0
	global_load_dwordx4 v[146:149], v[138:139], off offset:256
	s_waitcnt vmcnt(0)
	s_nop 0
	v_lshlrev_b32_e32 v138, 16, v130
	v_and_b32_e32 v139, 0xffff0000, v130
	v_lshlrev_b32_e32 v130, 16, v131
	v_and_b32_e32 v131, 0xffff0000, v131
	v_pk_fma_f32 v[112:113], v[130:131], s[18:19], v[112:113] op_sel_hi:[1,0,1]
	v_lshlrev_b32_e32 v130, 16, v132
	v_and_b32_e32 v131, 0xffff0000, v132
	v_lshlrev_b32_e32 v132, 16, v133
	v_and_b32_e32 v133, 0xffff0000, v133
	v_pk_fma_f32 v[98:99], v[130:131], s[18:19], v[98:99] op_sel_hi:[1,0,1]
	v_lshlrev_b32_e32 v130, 16, v134
	v_and_b32_e32 v131, 0xffff0000, v134
	v_pk_fma_f32 v[100:101], v[132:133], s[18:19], v[100:101] op_sel_hi:[1,0,1]
	v_lshlrev_b32_e32 v132, 16, v135
	v_and_b32_e32 v133, 0xffff0000, v135
	v_pk_fma_f32 v[86:87], v[130:131], s[18:19], v[86:87] op_sel_hi:[1,0,1]
	v_lshlrev_b32_e32 v130, 16, v136
	v_and_b32_e32 v131, 0xffff0000, v136
	v_pk_fma_f32 v[88:89], v[132:133], s[18:19], v[88:89] op_sel_hi:[1,0,1]
	v_lshlrev_b32_e32 v132, 16, v137
	v_and_b32_e32 v133, 0xffff0000, v137
	v_pk_fma_f32 v[70:71], v[130:131], s[18:19], v[70:71] op_sel_hi:[1,0,1]
	v_lshlrev_b32_e32 v130, 16, v150
	v_and_b32_e32 v131, 0xffff0000, v150
	v_pk_fma_f32 v[72:73], v[132:133], s[18:19], v[72:73] op_sel_hi:[1,0,1]
	v_lshlrev_b32_e32 v132, 16, v151
	v_and_b32_e32 v133, 0xffff0000, v151
	v_pk_fma_f32 v[82:83], v[130:131], s[18:19], v[82:83] op_sel_hi:[1,0,1]
	v_lshlrev_b32_e32 v130, 16, v152
	v_and_b32_e32 v131, 0xffff0000, v152
	v_pk_fma_f32 v[84:85], v[132:133], s[18:19], v[84:85] op_sel_hi:[1,0,1]
	v_lshlrev_b32_e32 v132, 16, v153
	v_and_b32_e32 v133, 0xffff0000, v153
	v_pk_fma_f32 v[66:67], v[130:131], s[18:19], v[66:67] op_sel_hi:[1,0,1]
	v_lshlrev_b32_e32 v130, 16, v154
	v_and_b32_e32 v131, 0xffff0000, v154
	v_pk_fma_f32 v[68:69], v[132:133], s[18:19], v[68:69] op_sel_hi:[1,0,1]
	v_lshlrev_b32_e32 v132, 16, v155
	v_and_b32_e32 v133, 0xffff0000, v155
	v_pk_fma_f32 v[54:55], v[130:131], s[18:19], v[54:55] op_sel_hi:[1,0,1]
	v_lshlrev_b32_e32 v130, 16, v156
	v_and_b32_e32 v131, 0xffff0000, v156
	v_pk_fma_f32 v[56:57], v[132:133], s[18:19], v[56:57] op_sel_hi:[1,0,1]
	v_lshlrev_b32_e32 v132, 16, v157
	v_and_b32_e32 v133, 0xffff0000, v157
	v_pk_fma_f32 v[46:47], v[130:131], s[18:19], v[46:47] op_sel_hi:[1,0,1]
	v_lshlrev_b32_e32 v130, 16, v158
	v_and_b32_e32 v131, 0xffff0000, v158
	v_pk_fma_f32 v[48:49], v[132:133], s[18:19], v[48:49] op_sel_hi:[1,0,1]
	v_lshlrev_b32_e32 v132, 16, v159
	v_and_b32_e32 v133, 0xffff0000, v159
	v_pk_fma_f32 v[130:131], v[130:131], s[18:19], v[50:51] op_sel_hi:[1,0,1]
	v_lshlrev_b32_e32 v50, 16, v160
	v_and_b32_e32 v51, 0xffff0000, v160
	v_pk_fma_f32 v[132:133], v[132:133], s[18:19], v[52:53] op_sel_hi:[1,0,1]
	v_lshlrev_b32_e32 v52, 16, v161
	v_and_b32_e32 v53, 0xffff0000, v161
	v_pk_fma_f32 v[134:135], v[50:51], s[18:19], v[42:43] op_sel_hi:[1,0,1]
	v_lshlrev_b32_e32 v42, 16, v168
	v_and_b32_e32 v43, 0xffff0000, v168
	v_pk_fma_f32 v[136:137], v[52:53], s[18:19], v[44:45] op_sel_hi:[1,0,1]
	v_lshlrev_b32_e32 v44, 16, v169
	v_and_b32_e32 v45, 0xffff0000, v169
	v_pk_fma_f32 v[34:35], v[42:43], s[18:19], v[34:35] op_sel_hi:[1,0,1]
	v_lshlrev_b32_e32 v42, 16, v170
	v_and_b32_e32 v43, 0xffff0000, v170
	v_pk_fma_f32 v[36:37], v[44:45], s[18:19], v[36:37] op_sel_hi:[1,0,1]
	v_lshlrev_b32_e32 v44, 16, v171
	v_and_b32_e32 v45, 0xffff0000, v171
	v_pk_fma_f32 v[22:23], v[42:43], s[18:19], v[22:23] op_sel_hi:[1,0,1]
	v_lshlrev_b32_e32 v42, 16, v140
	v_and_b32_e32 v43, 0xffff0000, v140
	v_pk_fma_f32 v[110:111], v[138:139], s[18:19], v[110:111] op_sel_hi:[1,0,1]
	v_pk_fma_f32 v[24:25], v[44:45], s[18:19], v[24:25] op_sel_hi:[1,0,1]
	v_lshlrev_b32_e32 v44, 16, v141
	v_and_b32_e32 v45, 0xffff0000, v141
	v_pk_fma_f32 v[138:139], v[42:43], s[18:19], v[30:31] op_sel_hi:[1,0,1]
	v_lshlrev_b32_e32 v30, 16, v142
	v_and_b32_e32 v31, 0xffff0000, v142
	v_pk_fma_f32 v[140:141], v[44:45], s[18:19], v[32:33] op_sel_hi:[1,0,1]
	v_lshlrev_b32_e32 v32, 16, v143
	v_and_b32_e32 v33, 0xffff0000, v143
	v_pk_fma_f32 v[142:143], v[30:31], s[18:19], v[18:19] op_sel_hi:[1,0,1]
	v_lshlrev_b32_e32 v18, 16, v146
	v_and_b32_e32 v19, 0xffff0000, v146
	v_pk_fma_f32 v[144:145], v[32:33], s[18:19], v[20:21] op_sel_hi:[1,0,1]
	v_lshlrev_b32_e32 v20, 16, v147
	v_and_b32_e32 v21, 0xffff0000, v147
	v_pk_fma_f32 v[6:7], v[18:19], s[18:19], v[6:7] op_sel_hi:[1,0,1]
	v_lshlrev_b32_e32 v18, 16, v148
	v_and_b32_e32 v19, 0xffff0000, v148
	v_pk_fma_f32 v[8:9], v[20:21], s[18:19], v[8:9] op_sel_hi:[1,0,1]
	v_lshlrev_b32_e32 v20, 16, v149
	v_and_b32_e32 v21, 0xffff0000, v149
	v_pk_fma_f32 v[2:3], v[18:19], s[18:19], v[2:3] op_sel_hi:[1,0,1]
	v_lshlrev_b64 v[18:19], 2, v[162:163]
	v_pk_fma_f32 v[4:5], v[20:21], s[18:19], v[4:5] op_sel_hi:[1,0,1]
	v_lshl_add_u64 v[30:31], s[4:5], 0, v[18:19]
	v_lshl_add_u64 v[50:51], s[6:7], 0, v[18:19]
	global_load_dwordx4 v[146:149], v[30:31], off offset:16
	global_load_dwordx4 v[154:157], v[30:31], off
	global_load_dwordx4 v[150:153], v[50:51], off offset:16
	global_load_dwordx4 v[158:161], v[50:51], off
	global_load_dwordx4 v[18:21], v[30:31], off offset:528
	global_load_dwordx4 v[42:45], v[30:31], off offset:512
	s_nop 0
	global_load_dwordx4 v[30:33], v[50:51], off offset:528
	s_nop 0
	global_load_dwordx4 v[50:53], v[50:51], off offset:512
	v_cmp_lt_i32_e32 vcc, v165, v167
	v_xor_b32_e32 v168, 32, v219
	v_mov_b32_e32 v169, v92
	v_cndmask_b32_e32 v165, v219, v165, vcc
	v_cmp_lt_i32_e32 vcc, v168, v167
	v_mov_b32_e32 v170, v90
	v_mov_b32_e32 v171, v93
	v_cndmask_b32_e32 v167, v219, v168, vcc
	v_mov_b32_e32 v168, v91
	v_pk_add_f32 v[168:169], v[168:169], v[170:171]
	v_mov_b32_e32 v170, v95
	v_mov_b32_e32 v171, v96
	v_mov_b32_e32 v173, v97
	v_pk_add_f32 v[170:171], v[170:171], v[172:173]
	v_add_f32_e32 v168, v168, v169
	v_pk_add_f32 v[170:171], v[170:171], v[170:171] op_sel_hi:[0,1]
	v_add_f32_e32 v169, 0, v168
	v_add_f32_e32 v173, v10, v11
	v_add_f32_e32 v175, v12, v13
	v_mov_b32_e32 v172, v14
	v_mov_b32_e32 v174, v15
	v_mov_b32_e32 v170, v16
	v_mov_b32_e32 v168, v17
	v_pk_add_f32 v[172:173], v[172:173], v[174:175]
	v_pk_add_f32 v[168:169], v[170:171], v[168:169]
	v_lshlrev_b32_e32 v165, 2, v165
	v_pk_add_f32 v[168:169], v[172:173], v[168:169]
	v_lshlrev_b32_e32 v167, 2, v167
	v_add_f32_e32 v168, v168, v169
	v_mov_b32_e32 v169, v168
	s_nop 1
	v_permlane16_swap_b32 v169, v168
	s_lshl_b32 s0, s12, 3
	s_add_i32 s0, s0, 0
	v_cmp_gt_u32_e32 vcc, 16, v166
	s_waitcnt lgkmcnt(0)
	v_add_f32_e32 v168, v168, v169
	v_mov_b32_e32 v169, v168
	s_nop 1
	v_permlane32_swap_b32 v169, v168
	s_waitcnt lgkmcnt(0)
	v_add_f32_e32 v169, v168, v169
	v_fmamk_f32 v170, v169, 0xbc800000, v93
	v_fmamk_f32 v172, v169, 0xbc800000, v91
	v_fmamk_f32 v168, v169, 0xbc800000, v92
	v_fmamk_f32 v171, v169, 0xbc800000, v90
	v_mul_f32_e32 v172, v172, v172
	v_mul_f32_e32 v170, v170, v170
	v_fmac_f32_e32 v172, v171, v171
	v_fmac_f32_e32 v170, v168, v168
	v_fmamk_f32 v171, v169, 0xbc800000, v97
	v_fmamk_f32 v173, v169, 0xbc800000, v95
	v_add_f32_e32 v168, v172, v170
	v_fmamk_f32 v170, v169, 0xbc800000, v96
	v_fmamk_f32 v172, v169, 0xbc800000, v94
	v_mul_f32_e32 v173, v173, v173
	v_mul_f32_e32 v171, v171, v171
	v_fmac_f32_e32 v173, v172, v172
	v_fmac_f32_e32 v171, v170, v170
	v_add_f32_e32 v170, v173, v171
	v_fmamk_f32 v171, v169, 0xbc800000, v13
	v_fmamk_f32 v173, v169, 0xbc800000, v11
	v_add_f32_e32 v168, v168, v170
	v_fmamk_f32 v170, v169, 0xbc800000, v12
	v_fmamk_f32 v172, v169, 0xbc800000, v10
	v_mul_f32_e32 v173, v173, v173
	v_mul_f32_e32 v171, v171, v171
	v_fmac_f32_e32 v173, v172, v172
	v_fmac_f32_e32 v171, v170, v170
	v_add_f32_e32 v170, v173, v171
	v_fmamk_f32 v171, v169, 0xbc800000, v17
	v_fmamk_f32 v173, v169, 0xbc800000, v15
	v_add_f32_e32 v168, v170, v168
	v_fmamk_f32 v170, v169, 0xbc800000, v16
	v_fmamk_f32 v172, v169, 0xbc800000, v14
	v_mul_f32_e32 v173, v173, v173
	v_mul_f32_e32 v171, v171, v171
	v_fmac_f32_e32 v173, v172, v172
	v_fmac_f32_e32 v171, v170, v170
	v_add_f32_e32 v170, v173, v171
	v_add_f32_e32 v168, v170, v168
	v_mov_b32_e32 v170, v168
	s_nop 1
	v_permlane16_swap_b32 v170, v168
	s_waitcnt lgkmcnt(0)
	v_add_f32_e32 v170, v168, v170
	v_mov_b32_e32 v171, v170
	s_nop 1
	v_permlane32_swap_b32 v171, v170
	v_lshl_add_u32 v168, v1, 5, s0
	s_and_saveexec_b64 s[0:1], vcc
	v_readlane_b32 s38, v255, 28
	v_readlane_b32 s39, v255, 29
	v_readlane_b32 s97, v255, 33
	v_readlane_b32 s42, v255, 32
	s_cbranch_execz .LBB0_658
	v_mul_f32_e32 v172, 0x3c800000, v169
	s_waitcnt lgkmcnt(0)
	v_add_f32_e32 v173, v170, v171
	ds_write_b64 v168, v[172:173]
.LBB0_658:
	s_or_b64 exec, exec, s[0:1]
	v_mov_b32_e32 v170, v103
	s_waitcnt lgkmcnt(0)
	v_mov_b32_e32 v171, v104
	v_mov_b32_e32 v172, v102
	v_mov_b32_e32 v173, v105
	v_pk_add_f32 v[170:171], v[170:171], v[172:173]
	v_mov_b32_e32 v172, v107
	v_mov_b32_e32 v173, v108
	v_mov_b32_e32 v174, v106
	v_mov_b32_e32 v175, v109
	v_pk_add_f32 v[172:173], v[172:173], v[174:175]
	v_add_f32_e32 v169, v170, v171
	v_pk_add_f32 v[172:173], v[172:173], v[172:173] op_sel_hi:[0,1]
	v_add_f32_e32 v171, 0, v169
	v_add_f32_e32 v175, v26, v27
	v_add_f32_e32 v177, v28, v29
	v_mov_b32_e32 v174, v38
	v_mov_b32_e32 v176, v39
	v_mov_b32_e32 v172, v40
	v_mov_b32_e32 v170, v41
	v_pk_add_f32 v[174:175], v[174:175], v[176:177]
	v_pk_add_f32 v[170:171], v[172:173], v[170:171]
	s_nop 0
	v_pk_add_f32 v[170:171], v[174:175], v[170:171]
	s_nop 0
	v_add_f32_e32 v169, v170, v171
	v_mov_b32_e32 v170, v169
	s_nop 1
	v_permlane16_swap_b32 v170, v169
	s_waitcnt lgkmcnt(0)
	v_add_f32_e32 v169, v169, v170
	v_mov_b32_e32 v170, v169
	s_nop 1
	v_permlane32_swap_b32 v170, v169
	s_waitcnt lgkmcnt(0)
	v_add_f32_e32 v169, v169, v170
	v_fmamk_f32 v171, v169, 0xbc800000, v105
	v_fmamk_f32 v173, v169, 0xbc800000, v103
	v_fmamk_f32 v170, v169, 0xbc800000, v104
	v_fmamk_f32 v172, v169, 0xbc800000, v102
	v_mul_f32_e32 v173, v173, v173
	v_mul_f32_e32 v171, v171, v171
	v_fmac_f32_e32 v173, v172, v172
	v_fmac_f32_e32 v171, v170, v170
	v_fmamk_f32 v172, v169, 0xbc800000, v109
	v_fmamk_f32 v174, v169, 0xbc800000, v107
	v_add_f32_e32 v170, v173, v171
	v_fmamk_f32 v171, v169, 0xbc800000, v108
	v_fmamk_f32 v173, v169, 0xbc800000, v106
	v_mul_f32_e32 v174, v174, v174
	v_mul_f32_e32 v172, v172, v172
	v_fmac_f32_e32 v174, v173, v173
	v_fmac_f32_e32 v172, v171, v171
	v_add_f32_e32 v171, v174, v172
	v_fmamk_f32 v172, v169, 0xbc800000, v29
	v_fmamk_f32 v174, v169, 0xbc800000, v27
	v_add_f32_e32 v170, v170, v171
	v_fmamk_f32 v171, v169, 0xbc800000, v28
	v_fmamk_f32 v173, v169, 0xbc800000, v26
	v_mul_f32_e32 v174, v174, v174
	v_mul_f32_e32 v172, v172, v172
	v_fmac_f32_e32 v174, v173, v173
	v_fmac_f32_e32 v172, v171, v171
	v_add_f32_e32 v171, v174, v172
	v_fmamk_f32 v172, v169, 0xbc800000, v41
	v_fmamk_f32 v174, v169, 0xbc800000, v39
	v_add_f32_e32 v170, v171, v170
	v_fmamk_f32 v171, v169, 0xbc800000, v40
	v_fmamk_f32 v173, v169, 0xbc800000, v38
	v_mul_f32_e32 v174, v174, v174
	v_mul_f32_e32 v172, v172, v172
	v_fmac_f32_e32 v174, v173, v173
	v_fmac_f32_e32 v172, v171, v171
	v_add_f32_e32 v171, v174, v172
	v_add_f32_e32 v170, v171, v170
	v_mov_b32_e32 v171, v170
	s_nop 1
	v_permlane16_swap_b32 v171, v170
	s_waitcnt lgkmcnt(0)
	v_add_f32_e32 v170, v170, v171
	v_mov_b32_e32 v171, v170
	s_nop 1
	v_permlane32_swap_b32 v171, v170
	s_and_saveexec_b64 s[0:1], vcc
	v_readlane_b32 s44, v255, 30
	v_readlane_b32 s45, v255, 31
	s_cbranch_execz .LBB0_660
	v_mul_f32_e32 v172, 0x3c800000, v169
	s_waitcnt lgkmcnt(0)
	v_add_f32_e32 v173, v170, v171
	ds_write_b64 v168, v[172:173] offset:512
.LBB0_660:
	s_or_b64 exec, exec, s[0:1]
	v_mov_b32_e32 v170, v115
	s_waitcnt lgkmcnt(0)
	v_mov_b32_e32 v171, v116
	v_mov_b32_e32 v172, v114
	v_mov_b32_e32 v173, v117
	v_pk_add_f32 v[170:171], v[170:171], v[172:173]
	v_mov_b32_e32 v172, v119
	v_mov_b32_e32 v173, v120
	v_mov_b32_e32 v174, v118
	v_mov_b32_e32 v175, v121
	v_pk_add_f32 v[172:173], v[172:173], v[174:175]
	v_add_f32_e32 v169, v170, v171
	v_pk_add_f32 v[172:173], v[172:173], v[172:173] op_sel_hi:[0,1]
	v_add_f32_e32 v171, 0, v169
	v_add_f32_e32 v175, v58, v59
	v_add_f32_e32 v177, v60, v61
	v_mov_b32_e32 v174, v62
	v_mov_b32_e32 v176, v63
	v_mov_b32_e32 v172, v64
	v_mov_b32_e32 v170, v65
	v_pk_add_f32 v[174:175], v[174:175], v[176:177]
	v_pk_add_f32 v[170:171], v[172:173], v[170:171]
	s_nop 0
	v_pk_add_f32 v[170:171], v[174:175], v[170:171]
	s_nop 0
	v_add_f32_e32 v169, v170, v171
	v_mov_b32_e32 v170, v169
	s_nop 1
	v_permlane16_swap_b32 v170, v169
	s_waitcnt lgkmcnt(0)
	v_add_f32_e32 v169, v169, v170
	v_mov_b32_e32 v170, v169
	s_nop 1
	v_permlane32_swap_b32 v170, v169
	s_waitcnt lgkmcnt(0)
	v_add_f32_e32 v169, v169, v170
	v_fmamk_f32 v171, v169, 0xbc800000, v117
	v_fmamk_f32 v173, v169, 0xbc800000, v115
	v_fmamk_f32 v170, v169, 0xbc800000, v116
	v_fmamk_f32 v172, v169, 0xbc800000, v114
	v_mul_f32_e32 v173, v173, v173
	v_mul_f32_e32 v171, v171, v171
	v_fmac_f32_e32 v173, v172, v172
	v_fmac_f32_e32 v171, v170, v170
	v_fmamk_f32 v172, v169, 0xbc800000, v121
	v_fmamk_f32 v174, v169, 0xbc800000, v119
	v_add_f32_e32 v170, v173, v171
	v_fmamk_f32 v171, v169, 0xbc800000, v120
	v_fmamk_f32 v173, v169, 0xbc800000, v118
	v_mul_f32_e32 v174, v174, v174
	v_mul_f32_e32 v172, v172, v172
	v_fmac_f32_e32 v174, v173, v173
	v_fmac_f32_e32 v172, v171, v171
	v_add_f32_e32 v171, v174, v172
	v_fmamk_f32 v172, v169, 0xbc800000, v61
	v_fmamk_f32 v174, v169, 0xbc800000, v59
	v_add_f32_e32 v170, v170, v171
	v_fmamk_f32 v171, v169, 0xbc800000, v60
	v_fmamk_f32 v173, v169, 0xbc800000, v58
	v_mul_f32_e32 v174, v174, v174
	v_mul_f32_e32 v172, v172, v172
	v_fmac_f32_e32 v174, v173, v173
	v_fmac_f32_e32 v172, v171, v171
	v_add_f32_e32 v171, v174, v172
	v_fmamk_f32 v172, v169, 0xbc800000, v65
	v_fmamk_f32 v174, v169, 0xbc800000, v63
	v_add_f32_e32 v170, v171, v170
	v_fmamk_f32 v171, v169, 0xbc800000, v64
	v_fmamk_f32 v173, v169, 0xbc800000, v62
	v_mul_f32_e32 v174, v174, v174
	v_mul_f32_e32 v172, v172, v172
	v_fmac_f32_e32 v174, v173, v173
	v_fmac_f32_e32 v172, v171, v171
	v_add_f32_e32 v171, v174, v172
	v_add_f32_e32 v170, v171, v170
	v_mov_b32_e32 v171, v170
	s_nop 1
	v_permlane16_swap_b32 v171, v170
	s_waitcnt lgkmcnt(0)
	v_add_f32_e32 v170, v170, v171
	v_mov_b32_e32 v171, v170
	s_nop 1
	v_permlane32_swap_b32 v171, v170
	s_and_saveexec_b64 s[0:1], vcc
	s_cbranch_execz .LBB0_662
	v_mul_f32_e32 v172, 0x3c800000, v169
	s_waitcnt lgkmcnt(0)
	v_add_f32_e32 v173, v170, v171
	ds_write_b64 v168, v[172:173] offset:1024
.LBB0_662:
	s_or_b64 exec, exec, s[0:1]
	v_mov_b32_e32 v170, v123
	s_waitcnt lgkmcnt(0)
	v_mov_b32_e32 v171, v124
	v_mov_b32_e32 v172, v122
	v_mov_b32_e32 v173, v125
	v_pk_add_f32 v[170:171], v[170:171], v[172:173]
	v_mov_b32_e32 v172, v127
	v_mov_b32_e32 v173, v128
	v_mov_b32_e32 v174, v126
	v_mov_b32_e32 v175, v129
	v_pk_add_f32 v[172:173], v[172:173], v[174:175]
	v_add_f32_e32 v169, v170, v171
	v_pk_add_f32 v[172:173], v[172:173], v[172:173] op_sel_hi:[0,1]
	v_add_f32_e32 v171, 0, v169
	v_add_f32_e32 v175, v74, v75
	v_add_f32_e32 v177, v76, v77
	v_mov_b32_e32 v174, v78
	v_mov_b32_e32 v176, v79
	v_mov_b32_e32 v172, v80
	v_mov_b32_e32 v170, v81
	v_pk_add_f32 v[174:175], v[174:175], v[176:177]
	v_pk_add_f32 v[170:171], v[172:173], v[170:171]
	s_nop 0
	v_pk_add_f32 v[170:171], v[174:175], v[170:171]
	s_nop 0
	v_add_f32_e32 v169, v170, v171
	v_mov_b32_e32 v170, v169
	s_nop 1
	v_permlane16_swap_b32 v170, v169
	s_waitcnt lgkmcnt(0)
	v_add_f32_e32 v169, v169, v170
	v_mov_b32_e32 v170, v169
	s_nop 1
	v_permlane32_swap_b32 v170, v169
	s_waitcnt lgkmcnt(0)
	v_add_f32_e32 v169, v169, v170
	v_fmamk_f32 v171, v169, 0xbc800000, v125
	v_fmamk_f32 v173, v169, 0xbc800000, v123
	v_fmamk_f32 v170, v169, 0xbc800000, v124
	v_fmamk_f32 v172, v169, 0xbc800000, v122
	v_mul_f32_e32 v173, v173, v173
	v_mul_f32_e32 v171, v171, v171
	v_fmac_f32_e32 v173, v172, v172
	v_fmac_f32_e32 v171, v170, v170
	v_fmamk_f32 v172, v169, 0xbc800000, v129
	v_fmamk_f32 v174, v169, 0xbc800000, v127
	v_add_f32_e32 v170, v173, v171
	v_fmamk_f32 v171, v169, 0xbc800000, v128
	v_fmamk_f32 v173, v169, 0xbc800000, v126
	v_mul_f32_e32 v174, v174, v174
	v_mul_f32_e32 v172, v172, v172
	v_fmac_f32_e32 v174, v173, v173
	v_fmac_f32_e32 v172, v171, v171
	v_add_f32_e32 v171, v174, v172
	v_fmamk_f32 v172, v169, 0xbc800000, v77
	v_fmamk_f32 v174, v169, 0xbc800000, v75
	v_add_f32_e32 v170, v170, v171
	v_fmamk_f32 v171, v169, 0xbc800000, v76
	v_fmamk_f32 v173, v169, 0xbc800000, v74
	v_mul_f32_e32 v174, v174, v174
	v_mul_f32_e32 v172, v172, v172
	v_fmac_f32_e32 v174, v173, v173
	v_fmac_f32_e32 v172, v171, v171
	v_add_f32_e32 v171, v174, v172
	v_fmamk_f32 v172, v169, 0xbc800000, v81
	v_fmamk_f32 v174, v169, 0xbc800000, v79
	v_add_f32_e32 v170, v171, v170
	v_fmamk_f32 v171, v169, 0xbc800000, v80
	v_fmamk_f32 v173, v169, 0xbc800000, v78
	v_mul_f32_e32 v174, v174, v174
	v_mul_f32_e32 v172, v172, v172
	v_fmac_f32_e32 v174, v173, v173
	v_fmac_f32_e32 v172, v171, v171
	v_add_f32_e32 v171, v174, v172
	v_add_f32_e32 v170, v171, v170
	v_mov_b32_e32 v171, v170
	s_nop 1
	v_permlane16_swap_b32 v171, v170
	s_waitcnt lgkmcnt(0)
	v_add_f32_e32 v170, v170, v171
	v_mov_b32_e32 v171, v170
	s_nop 1
	v_permlane32_swap_b32 v171, v170
	s_and_saveexec_b64 s[0:1], vcc
	s_cbranch_execz .LBB0_664
	v_mul_f32_e32 v172, 0x3c800000, v169
	s_waitcnt lgkmcnt(0)
	v_add_f32_e32 v173, v170, v171
	ds_write_b64 v168, v[172:173] offset:1536
.LBB0_664:
	s_or_b64 exec, exec, s[0:1]
	v_mov_b32_e32 v170, v111
	s_waitcnt lgkmcnt(0)
	v_mov_b32_e32 v171, v112
	v_mov_b32_e32 v172, v110
	v_mov_b32_e32 v173, v113
	v_pk_add_f32 v[170:171], v[170:171], v[172:173]
	v_mov_b32_e32 v172, v99
	v_mov_b32_e32 v173, v100
	v_mov_b32_e32 v174, v98
	v_mov_b32_e32 v175, v101
	v_pk_add_f32 v[172:173], v[172:173], v[174:175]
	v_add_f32_e32 v169, v170, v171
	v_pk_add_f32 v[172:173], v[172:173], v[172:173] op_sel_hi:[0,1]
	v_add_f32_e32 v171, 0, v169
	v_add_f32_e32 v175, v86, v87
	v_add_f32_e32 v177, v88, v89
	v_mov_b32_e32 v174, v70
	v_mov_b32_e32 v176, v71
	v_mov_b32_e32 v172, v72
	v_mov_b32_e32 v170, v73
	v_pk_add_f32 v[174:175], v[174:175], v[176:177]
	v_pk_add_f32 v[170:171], v[172:173], v[170:171]
	s_nop 0
	v_pk_add_f32 v[170:171], v[174:175], v[170:171]
	s_nop 0
	v_add_f32_e32 v169, v170, v171
	v_mov_b32_e32 v170, v169
	s_nop 1
	v_permlane16_swap_b32 v170, v169
	s_waitcnt lgkmcnt(0)
	v_add_f32_e32 v169, v169, v170
	v_mov_b32_e32 v170, v169
	s_nop 1
	v_permlane32_swap_b32 v170, v169
	s_waitcnt lgkmcnt(0)
	v_add_f32_e32 v169, v169, v170
	v_fmamk_f32 v171, v169, 0xbc800000, v113
	v_fmamk_f32 v173, v169, 0xbc800000, v111
	v_fmamk_f32 v170, v169, 0xbc800000, v112
	v_fmamk_f32 v172, v169, 0xbc800000, v110
	v_mul_f32_e32 v173, v173, v173
	v_mul_f32_e32 v171, v171, v171
	v_fmac_f32_e32 v173, v172, v172
	v_fmac_f32_e32 v171, v170, v170
	v_fmamk_f32 v172, v169, 0xbc800000, v101
	v_fmamk_f32 v174, v169, 0xbc800000, v99
	v_add_f32_e32 v170, v173, v171
	v_fmamk_f32 v171, v169, 0xbc800000, v100
	v_fmamk_f32 v173, v169, 0xbc800000, v98
	v_mul_f32_e32 v174, v174, v174
	v_mul_f32_e32 v172, v172, v172
	v_fmac_f32_e32 v174, v173, v173
	v_fmac_f32_e32 v172, v171, v171
	v_add_f32_e32 v171, v174, v172
	v_fmamk_f32 v172, v169, 0xbc800000, v89
	v_fmamk_f32 v174, v169, 0xbc800000, v87
	v_add_f32_e32 v170, v170, v171
	v_fmamk_f32 v171, v169, 0xbc800000, v88
	v_fmamk_f32 v173, v169, 0xbc800000, v86
	v_mul_f32_e32 v174, v174, v174
	v_mul_f32_e32 v172, v172, v172
	v_fmac_f32_e32 v174, v173, v173
	v_fmac_f32_e32 v172, v171, v171
	v_add_f32_e32 v171, v174, v172
	v_fmamk_f32 v172, v169, 0xbc800000, v73
	v_fmamk_f32 v174, v169, 0xbc800000, v71
	v_add_f32_e32 v170, v171, v170
	v_fmamk_f32 v171, v169, 0xbc800000, v72
	v_fmamk_f32 v173, v169, 0xbc800000, v70
	v_mul_f32_e32 v174, v174, v174
	v_mul_f32_e32 v172, v172, v172
	v_fmac_f32_e32 v174, v173, v173
	v_fmac_f32_e32 v172, v171, v171
	v_add_f32_e32 v171, v174, v172
	v_add_f32_e32 v170, v171, v170
	v_mov_b32_e32 v171, v170
	s_nop 1
	v_permlane16_swap_b32 v171, v170
	s_waitcnt lgkmcnt(0)
	v_add_f32_e32 v170, v170, v171
	v_mov_b32_e32 v171, v170
	s_nop 1
	v_permlane32_swap_b32 v171, v170
	s_and_saveexec_b64 s[0:1], vcc
	s_cbranch_execz .LBB0_666
	v_mul_f32_e32 v172, 0x3c800000, v169
	s_waitcnt lgkmcnt(0)
	v_add_f32_e32 v173, v170, v171
	ds_write_b64 v168, v[172:173] offset:4096
.LBB0_666:
	s_or_b64 exec, exec, s[0:1]
	v_mov_b32_e32 v170, v83
	s_waitcnt lgkmcnt(0)
	v_mov_b32_e32 v171, v84
	v_mov_b32_e32 v172, v82
	v_mov_b32_e32 v173, v85
	v_pk_add_f32 v[170:171], v[170:171], v[172:173]
	v_mov_b32_e32 v172, v67
	v_mov_b32_e32 v173, v68
	v_mov_b32_e32 v174, v66
	v_mov_b32_e32 v175, v69
	v_pk_add_f32 v[172:173], v[172:173], v[174:175]
	v_add_f32_e32 v169, v170, v171
	v_pk_add_f32 v[172:173], v[172:173], v[172:173] op_sel_hi:[0,1]
	v_add_f32_e32 v171, 0, v169
	v_add_f32_e32 v175, v54, v55
	v_add_f32_e32 v177, v56, v57
	v_mov_b32_e32 v174, v46
	v_mov_b32_e32 v176, v47
	v_mov_b32_e32 v172, v48
	v_mov_b32_e32 v170, v49
	v_pk_add_f32 v[174:175], v[174:175], v[176:177]
	v_pk_add_f32 v[170:171], v[172:173], v[170:171]
	s_nop 0
	v_pk_add_f32 v[170:171], v[174:175], v[170:171]
	s_nop 0
	v_add_f32_e32 v169, v170, v171
	v_mov_b32_e32 v170, v169
	s_nop 1
	v_permlane16_swap_b32 v170, v169
	s_waitcnt lgkmcnt(0)
	v_add_f32_e32 v169, v169, v170
	v_mov_b32_e32 v170, v169
	s_nop 1
	v_permlane32_swap_b32 v170, v169
	s_waitcnt lgkmcnt(0)
	v_add_f32_e32 v169, v169, v170
	v_fmamk_f32 v171, v169, 0xbc800000, v85
	v_fmamk_f32 v173, v169, 0xbc800000, v83
	v_fmamk_f32 v170, v169, 0xbc800000, v84
	v_fmamk_f32 v172, v169, 0xbc800000, v82
	v_mul_f32_e32 v173, v173, v173
	v_mul_f32_e32 v171, v171, v171
	v_fmac_f32_e32 v173, v172, v172
	v_fmac_f32_e32 v171, v170, v170
	v_fmamk_f32 v172, v169, 0xbc800000, v69
	v_fmamk_f32 v174, v169, 0xbc800000, v67
	v_add_f32_e32 v170, v173, v171
	v_fmamk_f32 v171, v169, 0xbc800000, v68
	v_fmamk_f32 v173, v169, 0xbc800000, v66
	v_mul_f32_e32 v174, v174, v174
	v_mul_f32_e32 v172, v172, v172
	v_fmac_f32_e32 v174, v173, v173
	v_fmac_f32_e32 v172, v171, v171
	v_add_f32_e32 v171, v174, v172
	v_fmamk_f32 v172, v169, 0xbc800000, v57
	v_fmamk_f32 v174, v169, 0xbc800000, v55
	v_add_f32_e32 v170, v170, v171
	v_fmamk_f32 v171, v169, 0xbc800000, v56
	v_fmamk_f32 v173, v169, 0xbc800000, v54
	v_mul_f32_e32 v174, v174, v174
	v_mul_f32_e32 v172, v172, v172
	v_fmac_f32_e32 v174, v173, v173
	v_fmac_f32_e32 v172, v171, v171
	v_add_f32_e32 v171, v174, v172
	v_fmamk_f32 v172, v169, 0xbc800000, v49
	v_fmamk_f32 v174, v169, 0xbc800000, v47
	v_add_f32_e32 v170, v171, v170
	v_fmamk_f32 v171, v169, 0xbc800000, v48
	v_fmamk_f32 v173, v169, 0xbc800000, v46
	v_mul_f32_e32 v174, v174, v174
	v_mul_f32_e32 v172, v172, v172
	v_fmac_f32_e32 v174, v173, v173
	v_fmac_f32_e32 v172, v171, v171
	v_add_f32_e32 v171, v174, v172
	v_add_f32_e32 v170, v171, v170
	v_mov_b32_e32 v171, v170
	s_nop 1
	v_permlane16_swap_b32 v171, v170
	s_waitcnt lgkmcnt(0)
	v_add_f32_e32 v170, v170, v171
	v_mov_b32_e32 v171, v170
	s_nop 1
	v_permlane32_swap_b32 v171, v170
	s_and_saveexec_b64 s[0:1], vcc
	s_cbranch_execz .LBB0_668
	v_mul_f32_e32 v172, 0x3c800000, v169
	s_waitcnt lgkmcnt(0)
	v_add_f32_e32 v173, v170, v171
	ds_write_b64 v168, v[172:173] offset:4608
.LBB0_668:
	s_or_b64 exec, exec, s[0:1]
	v_mov_b32_e32 v170, v131
	s_waitcnt lgkmcnt(0)
	v_mov_b32_e32 v171, v132
	v_mov_b32_e32 v172, v130
	v_mov_b32_e32 v173, v133
	v_pk_add_f32 v[170:171], v[170:171], v[172:173]
	v_mov_b32_e32 v172, v135
	v_mov_b32_e32 v173, v136
	v_mov_b32_e32 v174, v134
	v_mov_b32_e32 v175, v137
	v_pk_add_f32 v[172:173], v[172:173], v[174:175]
	v_add_f32_e32 v169, v170, v171
	v_pk_add_f32 v[172:173], v[172:173], v[172:173] op_sel_hi:[0,1]
	v_add_f32_e32 v171, 0, v169
	v_add_f32_e32 v175, v34, v35
	v_add_f32_e32 v177, v36, v37
	v_mov_b32_e32 v174, v22
	v_mov_b32_e32 v176, v23
	v_mov_b32_e32 v172, v24
	v_mov_b32_e32 v170, v25
	v_pk_add_f32 v[174:175], v[174:175], v[176:177]
	v_pk_add_f32 v[170:171], v[172:173], v[170:171]
	s_nop 0
	v_pk_add_f32 v[170:171], v[174:175], v[170:171]
	s_nop 0
	v_add_f32_e32 v169, v170, v171
	v_mov_b32_e32 v170, v169
	s_nop 1
	v_permlane16_swap_b32 v170, v169
	s_waitcnt lgkmcnt(0)
	v_add_f32_e32 v169, v169, v170
	v_mov_b32_e32 v170, v169
	s_nop 1
	v_permlane32_swap_b32 v170, v169
	s_waitcnt lgkmcnt(0)
	v_add_f32_e32 v169, v169, v170
	v_fmamk_f32 v171, v169, 0xbc800000, v133
	v_fmamk_f32 v173, v169, 0xbc800000, v131
	v_fmamk_f32 v170, v169, 0xbc800000, v132
	v_fmamk_f32 v172, v169, 0xbc800000, v130
	v_mul_f32_e32 v173, v173, v173
	v_mul_f32_e32 v171, v171, v171
	v_fmac_f32_e32 v173, v172, v172
	v_fmac_f32_e32 v171, v170, v170
	v_fmamk_f32 v172, v169, 0xbc800000, v137
	v_fmamk_f32 v174, v169, 0xbc800000, v135
	v_add_f32_e32 v170, v173, v171
	v_fmamk_f32 v171, v169, 0xbc800000, v136
	v_fmamk_f32 v173, v169, 0xbc800000, v134
	v_mul_f32_e32 v174, v174, v174
	v_mul_f32_e32 v172, v172, v172
	v_fmac_f32_e32 v174, v173, v173
	v_fmac_f32_e32 v172, v171, v171
	v_add_f32_e32 v171, v174, v172
	v_fmamk_f32 v172, v169, 0xbc800000, v37
	v_fmamk_f32 v174, v169, 0xbc800000, v35
	v_add_f32_e32 v170, v170, v171
	v_fmamk_f32 v171, v169, 0xbc800000, v36
	v_fmamk_f32 v173, v169, 0xbc800000, v34
	v_mul_f32_e32 v174, v174, v174
	v_mul_f32_e32 v172, v172, v172
	v_fmac_f32_e32 v174, v173, v173
	v_fmac_f32_e32 v172, v171, v171
	v_add_f32_e32 v171, v174, v172
	v_fmamk_f32 v172, v169, 0xbc800000, v25
	v_fmamk_f32 v174, v169, 0xbc800000, v23
	v_add_f32_e32 v170, v171, v170
	v_fmamk_f32 v171, v169, 0xbc800000, v24
	v_fmamk_f32 v173, v169, 0xbc800000, v22
	v_mul_f32_e32 v174, v174, v174
	v_mul_f32_e32 v172, v172, v172
	v_fmac_f32_e32 v174, v173, v173
	v_fmac_f32_e32 v172, v171, v171
	v_add_f32_e32 v171, v174, v172
	v_add_f32_e32 v170, v171, v170
	v_mov_b32_e32 v171, v170
	s_nop 1
	v_permlane16_swap_b32 v171, v170
	s_waitcnt lgkmcnt(0)
	v_add_f32_e32 v170, v170, v171
	v_mov_b32_e32 v171, v170
	s_nop 1
	v_permlane32_swap_b32 v171, v170
	s_and_saveexec_b64 s[0:1], vcc
	s_cbranch_execz .LBB0_670
	v_mul_f32_e32 v172, 0x3c800000, v169
	s_waitcnt lgkmcnt(0)
	v_add_f32_e32 v173, v170, v171
	ds_write_b64 v168, v[172:173] offset:5120
.LBB0_670:
	s_or_b64 exec, exec, s[0:1]
	v_mov_b32_e32 v170, v139
	s_waitcnt lgkmcnt(0)
	v_mov_b32_e32 v171, v140
	v_mov_b32_e32 v172, v138
	v_mov_b32_e32 v173, v141
	v_pk_add_f32 v[170:171], v[170:171], v[172:173]
	v_mov_b32_e32 v172, v143
	v_mov_b32_e32 v173, v144
	v_mov_b32_e32 v174, v142
	v_mov_b32_e32 v175, v145
	v_pk_add_f32 v[172:173], v[172:173], v[174:175]
	v_add_f32_e32 v169, v170, v171
	v_pk_add_f32 v[172:173], v[172:173], v[172:173] op_sel_hi:[0,1]
	v_add_f32_e32 v171, 0, v169
	v_add_f32_e32 v175, v6, v7
	v_add_f32_e32 v177, v8, v9
	v_mov_b32_e32 v174, v2
	v_mov_b32_e32 v176, v3
	v_mov_b32_e32 v172, v4
	v_mov_b32_e32 v170, v5
	v_pk_add_f32 v[174:175], v[174:175], v[176:177]
	v_pk_add_f32 v[170:171], v[172:173], v[170:171]
	s_nop 0
	v_pk_add_f32 v[170:171], v[174:175], v[170:171]
	s_nop 0
	v_add_f32_e32 v169, v170, v171
	v_mov_b32_e32 v170, v169
	s_nop 1
	v_permlane16_swap_b32 v170, v169
	s_waitcnt lgkmcnt(0)
	v_add_f32_e32 v169, v169, v170
	v_mov_b32_e32 v170, v169
	s_nop 1
	v_permlane32_swap_b32 v170, v169
	s_waitcnt lgkmcnt(0)
	v_add_f32_e32 v169, v169, v170
	v_fmamk_f32 v171, v169, 0xbc800000, v141
	v_fmamk_f32 v173, v169, 0xbc800000, v139
	v_fmamk_f32 v170, v169, 0xbc800000, v140
	v_fmamk_f32 v172, v169, 0xbc800000, v138
	v_mul_f32_e32 v173, v173, v173
	v_mul_f32_e32 v171, v171, v171
	v_fmac_f32_e32 v173, v172, v172
	v_fmac_f32_e32 v171, v170, v170
	v_fmamk_f32 v172, v169, 0xbc800000, v145
	v_fmamk_f32 v174, v169, 0xbc800000, v143
	v_add_f32_e32 v170, v173, v171
	v_fmamk_f32 v171, v169, 0xbc800000, v144
	v_fmamk_f32 v173, v169, 0xbc800000, v142
	v_mul_f32_e32 v174, v174, v174
	v_mul_f32_e32 v172, v172, v172
	v_fmac_f32_e32 v174, v173, v173
	v_fmac_f32_e32 v172, v171, v171
	v_add_f32_e32 v171, v174, v172
	v_fmamk_f32 v172, v169, 0xbc800000, v9
	v_fmamk_f32 v174, v169, 0xbc800000, v7
	v_add_f32_e32 v170, v170, v171
	v_fmamk_f32 v171, v169, 0xbc800000, v8
	v_fmamk_f32 v173, v169, 0xbc800000, v6
	v_mul_f32_e32 v174, v174, v174
	v_mul_f32_e32 v172, v172, v172
	v_fmac_f32_e32 v174, v173, v173
	v_fmac_f32_e32 v172, v171, v171
	v_add_f32_e32 v171, v174, v172
	v_fmamk_f32 v172, v169, 0xbc800000, v5
	v_fmamk_f32 v174, v169, 0xbc800000, v3
	v_add_f32_e32 v170, v171, v170
	v_fmamk_f32 v171, v169, 0xbc800000, v4
	v_fmamk_f32 v173, v169, 0xbc800000, v2
	v_mul_f32_e32 v174, v174, v174
	v_mul_f32_e32 v172, v172, v172
	v_fmac_f32_e32 v174, v173, v173
	v_fmac_f32_e32 v172, v171, v171
	v_add_f32_e32 v171, v174, v172
	v_add_f32_e32 v170, v171, v170
	v_mov_b32_e32 v165, v170
	s_nop 1
	v_permlane16_swap_b32 v165, v170
	s_waitcnt lgkmcnt(0)
	v_add_f32_e32 v165, v170, v165
	v_mov_b32_e32 v167, v165
	s_nop 1
	v_permlane32_swap_b32 v167, v165
	s_and_saveexec_b64 s[0:1], vcc
	s_cbranch_execz .LBB0_672
	v_mul_f32_e32 v170, 0x3c800000, v169
	s_waitcnt lgkmcnt(0)
	v_add_f32_e32 v171, v165, v167
	ds_write_b64 v168, v[170:171] offset:5632

.LBB0_749:
	s_add_u32 s20, s18, 0xfff80080
	s_addc_u32 s21, s19, -1
	s_add_i32 s58, 0, 0x10000
	v_add_u32_e32 v159, s58, v1
	ds_read_b128 v[160:163], v159
	ds_read_b128 v[164:167], v159 offset:1024
	ds_read_b128 v[168:171], v159 offset:2048
	ds_read_b128 v[172:175], v159 offset:3072
	s_cmp_eq_u32 s57, 28
	s_cselect_b32 s23, s39, s21
	s_cselect_b32 s22, s53, s20
	s_cselect_b32 s21, s31, s56
	s_cselect_b32 s20, s54, s55
	v_lshl_add_u64 v[212:213], s[18:19], 0, v[154:155]
	s_add_i32 m0, s44, 0xc000
	ds_read_b128 v[176:179], v158
	ds_read_b128 v[192:195], v158 offset:1024
	ds_read_b128 v[196:199], v158 offset:2048
	ds_read_b128 v[200:203], v158 offset:3072
	ds_read_b128 v[204:207], v158 offset:4096
	ds_read_b128 v[208:211], v158 offset:5120
	ds_read_b128 v[224:227], v158 offset:6144
	ds_read_b128 v[228:231], v158 offset:7168
	global_load_lds_dwordx4 v[212:213], off
	v_lshl_add_u64 v[212:213], s[18:19], 0, v[156:157]
	s_add_i32 m0, s44, 0xe000
	s_nop 0
	global_load_lds_dwordx4 v[212:213], off
	s_waitcnt lgkmcnt(8)
	s_barrier
	s_waitcnt lgkmcnt(0)
	s_setprio 1
	s_waitcnt lgkmcnt(0)
	v_mfma_f32_16x16x32_bf16 v[126:129], v[160:163], v[176:179], v[126:129]
	v_mfma_f32_16x16x32_bf16 v[122:125], v[168:171], v[176:179], v[122:125]
	v_mfma_f32_16x16x32_bf16 v[110:113], v[160:163], v[196:199], v[110:113]
	v_mfma_f32_16x16x32_bf16 v[106:109], v[168:171], v[196:199], v[106:109]
	v_mfma_f32_16x16x32_bf16 v[94:97], v[160:163], v[204:207], v[94:97]
	v_mfma_f32_16x16x32_bf16 v[90:93], v[168:171], v[204:207], v[90:93]
	v_mfma_f32_16x16x32_bf16 v[78:81], v[160:163], v[224:227], v[78:81]
	v_mfma_f32_16x16x32_bf16 v[74:77], v[168:171], v[224:227], v[74:77]
	v_mfma_f32_16x16x32_bf16 v[126:129], v[164:167], v[192:195], v[126:129]
	v_mfma_f32_16x16x32_bf16 v[122:125], v[172:175], v[192:195], v[122:125]
	v_mfma_f32_16x16x32_bf16 v[110:113], v[164:167], v[200:203], v[110:113]
	v_mfma_f32_16x16x32_bf16 v[106:109], v[172:175], v[200:203], v[106:109]
	v_mfma_f32_16x16x32_bf16 v[94:97], v[164:167], v[208:211], v[94:97]
	v_mfma_f32_16x16x32_bf16 v[90:93], v[172:175], v[208:211], v[90:93]
	v_mfma_f32_16x16x32_bf16 v[78:81], v[164:167], v[228:231], v[78:81]
	v_mfma_f32_16x16x32_bf16 v[74:77], v[172:175], v[228:231], v[74:77]
	s_setprio 0
	s_barrier
	s_add_i32 s82, 0, 0x14000
	s_add_i32 s58, s58, s29
	v_add_u32_e32 v159, s82, v1
	v_lshl_add_u64 v[212:213], s[20:21], 0, v[134:135]
	s_mov_b32 m0, s58
	ds_read_b128 v[232:235], v159
	ds_read_b128 v[236:239], v159 offset:1024
	ds_read_b128 v[240:243], v159 offset:2048
	ds_read_b128 v[244:247], v159 offset:3072
	global_load_lds_dwordx4 v[212:213], off
	v_lshl_add_u64 v[248:249], s[20:21], 0, v[130:131]
	s_add_i32 m0, s58, 0x2000
	s_nop 0
	global_load_lds_dwordx4 v[248:249], off
	s_barrier
	s_waitcnt lgkmcnt(0)
	s_setprio 1
	s_waitcnt lgkmcnt(0)
	v_mfma_f32_16x16x32_bf16 v[118:121], v[232:235], v[176:179], v[118:121]
	v_mfma_f32_16x16x32_bf16 v[114:117], v[240:243], v[176:179], v[114:117]
	v_mfma_f32_16x16x32_bf16 v[102:105], v[232:235], v[196:199], v[102:105]
	v_mfma_f32_16x16x32_bf16 v[98:101], v[240:243], v[196:199], v[98:101]
	v_mfma_f32_16x16x32_bf16 v[86:89], v[232:235], v[204:207], v[86:89]
	v_mfma_f32_16x16x32_bf16 v[82:85], v[240:243], v[204:207], v[82:85]
	v_mfma_f32_16x16x32_bf16 v[70:73], v[232:235], v[224:227], v[70:73]
	v_mfma_f32_16x16x32_bf16 v[66:69], v[240:243], v[224:227], v[66:69]
	v_mfma_f32_16x16x32_bf16 v[118:121], v[236:239], v[192:195], v[118:121]
	v_mfma_f32_16x16x32_bf16 v[114:117], v[244:247], v[192:195], v[114:117]
	v_mfma_f32_16x16x32_bf16 v[102:105], v[236:239], v[200:203], v[102:105]
	v_mfma_f32_16x16x32_bf16 v[98:101], v[244:247], v[200:203], v[98:101]
	v_mfma_f32_16x16x32_bf16 v[86:89], v[236:239], v[208:211], v[86:89]
	v_mfma_f32_16x16x32_bf16 v[82:85], v[244:247], v[208:211], v[82:85]
	v_mfma_f32_16x16x32_bf16 v[70:73], v[236:239], v[228:231], v[70:73]
	v_mfma_f32_16x16x32_bf16 v[66:69], v[244:247], v[228:231], v[66:69]
	s_setprio 0
	s_mov_b32 m0, s44
	v_lshl_add_u64 v[250:251], s[22:23], 0, v[136:137]
	s_barrier
	ds_read_b128 v[176:179], v158 offset:16384
	ds_read_b128 v[192:195], v158 offset:17408
	ds_read_b128 v[196:199], v158 offset:18432
	ds_read_b128 v[200:203], v158 offset:19456
	ds_read_b128 v[204:207], v158 offset:20480
	ds_read_b128 v[208:211], v158 offset:21504
	ds_read_b128 v[224:227], v158 offset:22528
	ds_read_b128 v[228:231], v158 offset:23552
	global_load_lds_dwordx4 v[250:251], off
	v_lshl_add_u64 v[222:223], s[22:23], 0, v[132:133]
	s_mov_b32 m0, s45
	s_nop 0
	global_load_lds_dwordx4 v[222:223], off
	s_barrier
	s_waitcnt lgkmcnt(0)
	s_setprio 1
	s_waitcnt lgkmcnt(0)
	v_mfma_f32_16x16x32_bf16 v[62:65], v[160:163], v[176:179], v[62:65]
	v_mfma_f32_16x16x32_bf16 v[58:61], v[168:171], v[176:179], v[58:61]
	v_mfma_f32_16x16x32_bf16 v[46:49], v[160:163], v[196:199], v[46:49]
	v_mfma_f32_16x16x32_bf16 v[42:45], v[168:171], v[196:199], v[42:45]
	v_mfma_f32_16x16x32_bf16 v[30:33], v[160:163], v[204:207], v[30:33]
	v_mfma_f32_16x16x32_bf16 v[26:29], v[168:171], v[204:207], v[26:29]
	v_mfma_f32_16x16x32_bf16 v[14:17], v[160:163], v[224:227], v[14:17]
	v_mfma_f32_16x16x32_bf16 v[10:13], v[168:171], v[224:227], v[10:13]
	v_mfma_f32_16x16x32_bf16 v[62:65], v[164:167], v[192:195], v[62:65]
	v_mfma_f32_16x16x32_bf16 v[58:61], v[172:175], v[192:195], v[58:61]
	v_mfma_f32_16x16x32_bf16 v[46:49], v[164:167], v[200:203], v[46:49]
	v_mfma_f32_16x16x32_bf16 v[42:45], v[172:175], v[200:203], v[42:45]
	v_mfma_f32_16x16x32_bf16 v[30:33], v[164:167], v[208:211], v[30:33]
	v_mfma_f32_16x16x32_bf16 v[26:29], v[172:175], v[208:211], v[26:29]
	v_mfma_f32_16x16x32_bf16 v[14:17], v[164:167], v[228:231], v[14:17]
	v_mfma_f32_16x16x32_bf16 v[10:13], v[172:175], v[228:231], v[10:13]
	s_setprio 0
	s_barrier
	s_add_u32 s58, s20, 0x80000
	s_addc_u32 s59, s21, 0
	s_add_i32 s82, s82, s29
	v_lshl_add_u64 v[160:161], s[58:59], 0, v[134:135]
	s_mov_b32 m0, s82
	s_nop 0
	global_load_lds_dwordx4 v[160:161], off
	v_lshl_add_u64 v[160:161], s[58:59], 0, v[130:131]
	s_add_i32 m0, s82, 0x2000
	s_nop 0
	global_load_lds_dwordx4 v[160:161], off
	s_waitcnt vmcnt(6)
	s_barrier
	s_setprio 1
	v_mfma_f32_16x16x32_bf16 v[54:57], v[232:235], v[176:179], v[54:57]
	v_mfma_f32_16x16x32_bf16 v[50:53], v[240:243], v[176:179], v[50:53]
	v_mfma_f32_16x16x32_bf16 v[38:41], v[232:235], v[196:199], v[38:41]
	v_mfma_f32_16x16x32_bf16 v[34:37], v[240:243], v[196:199], v[34:37]
	v_mfma_f32_16x16x32_bf16 v[22:25], v[232:235], v[204:207], v[22:25]
	v_mfma_f32_16x16x32_bf16 v[18:21], v[240:243], v[204:207], v[18:21]
	v_mfma_f32_16x16x32_bf16 v[6:9], v[232:235], v[224:227], v[6:9]
	v_mfma_f32_16x16x32_bf16 v[2:5], v[240:243], v[224:227], v[2:5]
	v_mfma_f32_16x16x32_bf16 v[54:57], v[236:239], v[192:195], v[54:57]
	v_mfma_f32_16x16x32_bf16 v[50:53], v[244:247], v[192:195], v[50:53]
	v_mfma_f32_16x16x32_bf16 v[38:41], v[236:239], v[200:203], v[38:41]
	v_mfma_f32_16x16x32_bf16 v[34:37], v[244:247], v[200:203], v[34:37]
	v_mfma_f32_16x16x32_bf16 v[22:25], v[236:239], v[208:211], v[22:25]
	v_mfma_f32_16x16x32_bf16 v[18:21], v[244:247], v[208:211], v[18:21]
	v_mfma_f32_16x16x32_bf16 v[6:9], v[236:239], v[228:231], v[6:9]
	v_mfma_f32_16x16x32_bf16 v[2:5], v[244:247], v[228:231], v[2:5]
	s_setprio 0
	s_add_i32 s58, 0, 0x18000
	v_add_u32_e32 v159, s58, v1
	s_barrier
	ds_read_b128 v[160:163], v159
	ds_read_b128 v[164:167], v159 offset:1024
	ds_read_b128 v[168:171], v159 offset:2048
	ds_read_b128 v[172:175], v159 offset:3072
	s_add_u32 s22, s22, 0x80000
	s_addc_u32 s23, s23, 0
	s_mov_b32 m0, s46
	v_lshl_add_u64 v[232:233], s[22:23], 0, v[136:137]
	ds_read_b128 v[176:179], v158 offset:32768
	ds_read_b128 v[192:195], v158 offset:33792
	ds_read_b128 v[196:199], v158 offset:34816
	ds_read_b128 v[200:203], v158 offset:35840
	ds_read_b128 v[204:207], v158 offset:36864
	ds_read_b128 v[208:211], v158 offset:37888
	ds_read_b128 v[224:227], v158 offset:38912
	ds_read_b128 v[228:231], v158 offset:39936
	global_load_lds_dwordx4 v[232:233], off
	v_lshl_add_u64 v[232:233], s[22:23], 0, v[132:133]
	s_mov_b32 m0, s47
	s_nop 0
	global_load_lds_dwordx4 v[232:233], off
	s_waitcnt lgkmcnt(8)
	s_barrier
	s_waitcnt lgkmcnt(0)
	s_setprio 1
	s_waitcnt lgkmcnt(0)
	v_mfma_f32_16x16x32_bf16 v[126:129], v[160:163], v[176:179], v[126:129]
	v_mfma_f32_16x16x32_bf16 v[122:125], v[168:171], v[176:179], v[122:125]
	v_mfma_f32_16x16x32_bf16 v[110:113], v[160:163], v[196:199], v[110:113]
	v_mfma_f32_16x16x32_bf16 v[106:109], v[168:171], v[196:199], v[106:109]
	v_mfma_f32_16x16x32_bf16 v[94:97], v[160:163], v[204:207], v[94:97]
	v_mfma_f32_16x16x32_bf16 v[90:93], v[168:171], v[204:207], v[90:93]
	v_mfma_f32_16x16x32_bf16 v[78:81], v[160:163], v[224:227], v[78:81]
	v_mfma_f32_16x16x32_bf16 v[74:77], v[168:171], v[224:227], v[74:77]
	v_mfma_f32_16x16x32_bf16 v[126:129], v[164:167], v[192:195], v[126:129]
	v_mfma_f32_16x16x32_bf16 v[122:125], v[172:175], v[192:195], v[122:125]
	v_mfma_f32_16x16x32_bf16 v[110:113], v[164:167], v[200:203], v[110:113]
	v_mfma_f32_16x16x32_bf16 v[106:109], v[172:175], v[200:203], v[106:109]
	v_mfma_f32_16x16x32_bf16 v[94:97], v[164:167], v[208:211], v[94:97]
	v_mfma_f32_16x16x32_bf16 v[90:93], v[172:175], v[208:211], v[90:93]
	v_mfma_f32_16x16x32_bf16 v[78:81], v[164:167], v[228:231], v[78:81]
	v_mfma_f32_16x16x32_bf16 v[74:77], v[172:175], v[228:231], v[74:77]
	s_setprio 0
	s_barrier
	s_add_i32 s22, 0, 0x1c000
	s_add_i32 s23, s58, s29
	v_add_u32_e32 v159, s22, v1
	v_lshl_add_u64 v[212:213], v[212:213], 0, s[78:79]
	s_mov_b32 m0, s23
	ds_read_b128 v[232:235], v159
	ds_read_b128 v[236:239], v159 offset:1024
	ds_read_b128 v[240:243], v159 offset:2048
	ds_read_b128 v[244:247], v159 offset:3072
	global_load_lds_dwordx4 v[212:213], off
	v_lshl_add_u64 v[212:213], v[248:249], 0, s[78:79]
	s_add_i32 m0, s23, 0x2000
	s_nop 0
	global_load_lds_dwordx4 v[212:213], off
	s_barrier
	s_waitcnt lgkmcnt(0)
	s_setprio 1
	s_waitcnt lgkmcnt(0)
	v_mfma_f32_16x16x32_bf16 v[118:121], v[232:235], v[176:179], v[118:121]
	v_mfma_f32_16x16x32_bf16 v[114:117], v[240:243], v[176:179], v[114:117]
	v_mfma_f32_16x16x32_bf16 v[102:105], v[232:235], v[196:199], v[102:105]
	v_mfma_f32_16x16x32_bf16 v[98:101], v[240:243], v[196:199], v[98:101]
	v_mfma_f32_16x16x32_bf16 v[86:89], v[232:235], v[204:207], v[86:89]
	v_mfma_f32_16x16x32_bf16 v[82:85], v[240:243], v[204:207], v[82:85]
	v_mfma_f32_16x16x32_bf16 v[70:73], v[232:235], v[224:227], v[70:73]
	v_mfma_f32_16x16x32_bf16 v[66:69], v[240:243], v[224:227], v[66:69]
	v_mfma_f32_16x16x32_bf16 v[118:121], v[236:239], v[192:195], v[118:121]
	v_mfma_f32_16x16x32_bf16 v[114:117], v[244:247], v[192:195], v[114:117]
	v_mfma_f32_16x16x32_bf16 v[102:105], v[236:239], v[200:203], v[102:105]
	v_mfma_f32_16x16x32_bf16 v[98:101], v[244:247], v[200:203], v[98:101]
	v_mfma_f32_16x16x32_bf16 v[86:89], v[236:239], v[208:211], v[86:89]
	v_mfma_f32_16x16x32_bf16 v[82:85], v[244:247], v[208:211], v[82:85]
	v_mfma_f32_16x16x32_bf16 v[70:73], v[236:239], v[228:231], v[70:73]
	v_mfma_f32_16x16x32_bf16 v[66:69], v[244:247], v[228:231], v[66:69]
	s_setprio 0
	s_mov_b32 m0, s48
	v_lshl_add_u64 v[212:213], v[250:251], 0, s[78:79]
	s_barrier
	ds_read_b128 v[176:179], v158 offset:49152
	ds_read_b128 v[192:195], v158 offset:50176
	ds_read_b128 v[196:199], v158 offset:51200
	ds_read_b128 v[200:203], v158 offset:52224
	ds_read_b128 v[204:207], v158 offset:53248
	ds_read_b128 v[208:211], v158 offset:54272
	ds_read_b128 v[224:227], v158 offset:55296
	ds_read_b128 v[228:231], v158 offset:56320
	global_load_lds_dwordx4 v[212:213], off
	v_lshl_add_u64 v[212:213], v[222:223], 0, s[78:79]
	s_mov_b32 m0, s49
	s_nop 0
	global_load_lds_dwordx4 v[212:213], off
	s_barrier
	s_waitcnt lgkmcnt(0)
	s_setprio 1
	s_waitcnt lgkmcnt(0)
	v_mfma_f32_16x16x32_bf16 v[62:65], v[160:163], v[176:179], v[62:65]
	v_mfma_f32_16x16x32_bf16 v[58:61], v[168:171], v[176:179], v[58:61]
	v_mfma_f32_16x16x32_bf16 v[46:49], v[160:163], v[196:199], v[46:49]
	v_mfma_f32_16x16x32_bf16 v[42:45], v[168:171], v[196:199], v[42:45]
	v_mfma_f32_16x16x32_bf16 v[30:33], v[160:163], v[204:207], v[30:33]
	v_mfma_f32_16x16x32_bf16 v[26:29], v[168:171], v[204:207], v[26:29]
	v_mfma_f32_16x16x32_bf16 v[14:17], v[160:163], v[224:227], v[14:17]
	v_mfma_f32_16x16x32_bf16 v[10:13], v[168:171], v[224:227], v[10:13]
	v_mfma_f32_16x16x32_bf16 v[62:65], v[164:167], v[192:195], v[62:65]
	v_mfma_f32_16x16x32_bf16 v[58:61], v[172:175], v[192:195], v[58:61]
	v_mfma_f32_16x16x32_bf16 v[46:49], v[164:167], v[200:203], v[46:49]
	v_mfma_f32_16x16x32_bf16 v[42:45], v[172:175], v[200:203], v[42:45]
	v_mfma_f32_16x16x32_bf16 v[30:33], v[164:167], v[208:211], v[30:33]
	v_mfma_f32_16x16x32_bf16 v[26:29], v[172:175], v[208:211], v[26:29]
	v_mfma_f32_16x16x32_bf16 v[14:17], v[164:167], v[228:231], v[14:17]
	v_mfma_f32_16x16x32_bf16 v[10:13], v[172:175], v[228:231], v[10:13]
	s_setprio 0
	s_barrier
	s_add_u32 s20, s20, 0x80080
	s_addc_u32 s21, s21, 0
	s_add_i32 s22, s22, s29
	v_lshl_add_u64 v[160:161], s[20:21], 0, v[134:135]
	s_mov_b32 m0, s22
	s_nop 0
	global_load_lds_dwordx4 v[160:161], off
	v_lshl_add_u64 v[160:161], s[20:21], 0, v[130:131]
	s_add_i32 m0, s22, 0x2000
	s_nop 0
	global_load_lds_dwordx4 v[160:161], off
	s_waitcnt vmcnt(6)
	s_barrier
	s_setprio 1
	v_mfma_f32_16x16x32_bf16 v[54:57], v[232:235], v[176:179], v[54:57]
	v_mfma_f32_16x16x32_bf16 v[50:53], v[240:243], v[176:179], v[50:53]
	v_mfma_f32_16x16x32_bf16 v[38:41], v[232:235], v[196:199], v[38:41]
	v_mfma_f32_16x16x32_bf16 v[34:37], v[240:243], v[196:199], v[34:37]
	v_mfma_f32_16x16x32_bf16 v[22:25], v[232:235], v[204:207], v[22:25]
	v_mfma_f32_16x16x32_bf16 v[18:21], v[240:243], v[204:207], v[18:21]
	v_mfma_f32_16x16x32_bf16 v[6:9], v[232:235], v[224:227], v[6:9]
	v_mfma_f32_16x16x32_bf16 v[2:5], v[240:243], v[224:227], v[2:5]
	v_mfma_f32_16x16x32_bf16 v[54:57], v[236:239], v[192:195], v[54:57]
	v_mfma_f32_16x16x32_bf16 v[50:53], v[244:247], v[192:195], v[50:53]
	v_mfma_f32_16x16x32_bf16 v[38:41], v[236:239], v[200:203], v[38:41]
	v_mfma_f32_16x16x32_bf16 v[34:37], v[244:247], v[200:203], v[34:37]
	v_mfma_f32_16x16x32_bf16 v[22:25], v[236:239], v[208:211], v[22:25]
	v_mfma_f32_16x16x32_bf16 v[18:21], v[244:247], v[208:211], v[18:21]
	v_mfma_f32_16x16x32_bf16 v[6:9], v[236:239], v[228:231], v[6:9]
	v_mfma_f32_16x16x32_bf16 v[2:5], v[244:247], v[228:231], v[2:5]
	s_setprio 0
	s_add_i32 s57, s57, 2
	s_add_u32 s18, s18, 0x100
	s_addc_u32 s19, s19, 0
	s_add_u32 s55, s55, 0x100
	s_addc_u32 s56, s56, 0
	s_cmp_gt_u32 s57, 29
	s_barrier
	s_cbranch_scc0 .LBB0_749
	s_lshl_b32 s18, s52, 5
	s_add_i32 s18, s18, s51
	v_max_f32_e32 v122, 0, v122
	v_max_f32_e32 v123, 0, v123
	s_ashr_i32 s19, s18, 31
	v_pk_mul_f32 v[162:163], v[122:123], v[122:123]
	v_max_f32_e32 v123, v124, v124
	s_lshl_b64 s[18:19], s[18:19], 17
	v_max_f32_e32 v122, v128, v128
	v_max_f32_e32 v124, 0, v123
	v_max_f32_e32 v123, v129, v129
	s_add_u32 s18, s68, s18
	v_max_f32_e32 v126, 0, v126
	v_max_f32_e32 v127, 0, v127
	v_max_f32_e32 v122, 0, v122
	v_max_f32_e32 v123, 0, v123
	v_max_f32_e32 v125, 0, v125
	s_addc_u32 s19, s69, s19
	v_pk_mul_f32 v[126:127], v[126:127], v[126:127]
	v_pk_mul_f32 v[128:129], v[122:123], v[122:123]
	v_pk_mul_f32 v[164:165], v[124:125], v[124:125]
	v_lshl_add_u64 v[160:161], v[138:139], 1, s[18:19]
	v_cvt_pk_bf16_f32 v122, v126, v127
	v_cvt_pk_bf16_f32 v123, v128, v129
	v_cvt_pk_bf16_f32 v124, v162, v163
	v_cvt_pk_bf16_f32 v125, v164, v165
	v_max_f32_e32 v114, 0, v114
	v_max_f32_e32 v115, 0, v115
	global_store_dwordx4 v[160:161], v[122:125], off
	v_max_f32_e32 v118, v118, v118
	v_max_f32_e32 v119, v119, v119
	v_pk_mul_f32 v[122:123], v[114:115], v[114:115]
	v_max_f32_e32 v115, v116, v116
	v_max_f32_e32 v114, v120, v120
	v_max_f32_e32 v116, 0, v115
	v_max_f32_e32 v115, v121, v121
	v_max_f32_e32 v118, 0, v118
	v_max_f32_e32 v119, 0, v119
	v_max_f32_e32 v114, 0, v114
	v_max_f32_e32 v115, 0, v115
	v_max_f32_e32 v117, 0, v117
	v_pk_mul_f32 v[118:119], v[118:119], v[118:119]
	v_pk_mul_f32 v[120:121], v[114:115], v[114:115]
	v_pk_mul_f32 v[124:125], v[116:117], v[116:117]
	v_cvt_pk_bf16_f32 v114, v118, v119
	v_cvt_pk_bf16_f32 v115, v120, v121
	v_cvt_pk_bf16_f32 v116, v122, v123
	v_cvt_pk_bf16_f32 v117, v124, v125
	v_max_f32_e32 v106, 0, v106
	v_max_f32_e32 v107, 0, v107
	global_store_dwordx4 v[160:161], v[114:117], off offset:256
	v_max_f32_e32 v110, v110, v110
	v_max_f32_e32 v111, v111, v111
	v_pk_mul_f32 v[116:117], v[106:107], v[106:107]
	v_max_f32_e32 v107, v108, v108
	v_max_f32_e32 v106, v112, v112
	v_max_f32_e32 v108, 0, v107
	v_max_f32_e32 v107, v113, v113
	v_max_f32_e32 v110, 0, v110
	v_max_f32_e32 v111, 0, v111
	v_max_f32_e32 v106, 0, v106
	v_max_f32_e32 v107, 0, v107
	v_max_f32_e32 v109, 0, v109
	v_pk_mul_f32 v[110:111], v[110:111], v[110:111]
	v_pk_mul_f32 v[112:113], v[106:107], v[106:107]
	v_pk_mul_f32 v[118:119], v[108:109], v[108:109]
	v_lshl_add_u64 v[114:115], v[140:141], 1, s[18:19]
	v_cvt_pk_bf16_f32 v106, v110, v111
	v_cvt_pk_bf16_f32 v107, v112, v113
	v_cvt_pk_bf16_f32 v108, v116, v117
	v_cvt_pk_bf16_f32 v109, v118, v119
	v_max_f32_e32 v98, 0, v98
	v_max_f32_e32 v99, 0, v99
	global_store_dwordx4 v[114:115], v[106:109], off
	v_max_f32_e32 v102, v102, v102
	v_max_f32_e32 v103, v103, v103
	v_pk_mul_f32 v[106:107], v[98:99], v[98:99]
	v_max_f32_e32 v99, v100, v100
	v_max_f32_e32 v98, v104, v104
	v_max_f32_e32 v100, 0, v99
	v_max_f32_e32 v99, v105, v105
	v_max_f32_e32 v102, 0, v102
	v_max_f32_e32 v103, 0, v103
	v_max_f32_e32 v98, 0, v98
	v_max_f32_e32 v99, 0, v99
	v_max_f32_e32 v101, 0, v101
	v_pk_mul_f32 v[102:103], v[102:103], v[102:103]
	v_pk_mul_f32 v[104:105], v[98:99], v[98:99]
	v_pk_mul_f32 v[108:109], v[100:101], v[100:101]
	v_cvt_pk_bf16_f32 v98, v102, v103
	v_cvt_pk_bf16_f32 v99, v104, v105
	v_cvt_pk_bf16_f32 v100, v106, v107
	v_cvt_pk_bf16_f32 v101, v108, v109
	v_max_f32_e32 v90, 0, v90
	v_max_f32_e32 v91, 0, v91
	global_store_dwordx4 v[114:115], v[98:101], off offset:256
	v_max_f32_e32 v94, v94, v94
	v_max_f32_e32 v95, v95, v95
	v_pk_mul_f32 v[100:101], v[90:91], v[90:91]
	v_max_f32_e32 v91, v92, v92
	v_max_f32_e32 v90, v96, v96
	v_max_f32_e32 v92, 0, v91
	v_max_f32_e32 v91, v97, v97
	v_max_f32_e32 v94, 0, v94
	v_max_f32_e32 v95, 0, v95
	v_max_f32_e32 v90, 0, v90
	v_max_f32_e32 v91, 0, v91
	v_max_f32_e32 v93, 0, v93
	v_pk_mul_f32 v[94:95], v[94:95], v[94:95]
	v_pk_mul_f32 v[96:97], v[90:91], v[90:91]
	v_pk_mul_f32 v[102:103], v[92:93], v[92:93]
	v_lshl_add_u64 v[98:99], v[142:143], 1, s[18:19]
	v_cvt_pk_bf16_f32 v90, v94, v95
	v_cvt_pk_bf16_f32 v91, v96, v97
	v_cvt_pk_bf16_f32 v92, v100, v101
	v_cvt_pk_bf16_f32 v93, v102, v103
	v_max_f32_e32 v82, 0, v82
	v_max_f32_e32 v83, 0, v83
	global_store_dwordx4 v[98:99], v[90:93], off
	v_max_f32_e32 v86, v86, v86
	v_max_f32_e32 v87, v87, v87
	v_pk_mul_f32 v[90:91], v[82:83], v[82:83]
	v_max_f32_e32 v83, v84, v84
	v_max_f32_e32 v82, v88, v88
	v_max_f32_e32 v84, 0, v83
	v_max_f32_e32 v83, v89, v89
	v_max_f32_e32 v86, 0, v86
	v_max_f32_e32 v87, 0, v87
	v_max_f32_e32 v82, 0, v82
	v_max_f32_e32 v83, 0, v83
	v_max_f32_e32 v85, 0, v85
	v_pk_mul_f32 v[86:87], v[86:87], v[86:87]
	v_pk_mul_f32 v[88:89], v[82:83], v[82:83]
	v_pk_mul_f32 v[92:93], v[84:85], v[84:85]
	v_cvt_pk_bf16_f32 v82, v86, v87
	v_cvt_pk_bf16_f32 v83, v88, v89
	v_cvt_pk_bf16_f32 v84, v90, v91
	v_cvt_pk_bf16_f32 v85, v92, v93
	v_max_f32_e32 v74, 0, v74
	v_max_f32_e32 v75, 0, v75
	global_store_dwordx4 v[98:99], v[82:85], off offset:256
	v_max_f32_e32 v78, v78, v78
	v_max_f32_e32 v79, v79, v79
	v_pk_mul_f32 v[84:85], v[74:75], v[74:75]
	v_max_f32_e32 v75, v76, v76
	v_max_f32_e32 v74, v80, v80
	v_max_f32_e32 v76, 0, v75
	v_max_f32_e32 v75, v81, v81
	v_max_f32_e32 v78, 0, v78
	v_max_f32_e32 v79, 0, v79
	v_max_f32_e32 v74, 0, v74
	v_max_f32_e32 v75, 0, v75
	v_max_f32_e32 v77, 0, v77
	v_pk_mul_f32 v[78:79], v[78:79], v[78:79]
	v_pk_mul_f32 v[80:81], v[74:75], v[74:75]
	v_pk_mul_f32 v[86:87], v[76:77], v[76:77]
	v_lshl_add_u64 v[82:83], v[144:145], 1, s[18:19]
	v_cvt_pk_bf16_f32 v74, v78, v79
	v_cvt_pk_bf16_f32 v75, v80, v81
	v_cvt_pk_bf16_f32 v76, v84, v85
	v_cvt_pk_bf16_f32 v77, v86, v87
	v_max_f32_e32 v66, 0, v66
	v_max_f32_e32 v67, 0, v67
	global_store_dwordx4 v[82:83], v[74:77], off
	v_max_f32_e32 v70, v70, v70
	v_max_f32_e32 v71, v71, v71
	v_pk_mul_f32 v[74:75], v[66:67], v[66:67]
	v_max_f32_e32 v67, v68, v68
	v_max_f32_e32 v66, v72, v72
	v_max_f32_e32 v68, 0, v67
	v_max_f32_e32 v67, v73, v73
	v_max_f32_e32 v70, 0, v70
	v_max_f32_e32 v71, 0, v71
	v_max_f32_e32 v66, 0, v66
	v_max_f32_e32 v67, 0, v67
	v_max_f32_e32 v69, 0, v69
	v_pk_mul_f32 v[70:71], v[70:71], v[70:71]
	v_pk_mul_f32 v[72:73], v[66:67], v[66:67]
	v_pk_mul_f32 v[76:77], v[68:69], v[68:69]
	v_cvt_pk_bf16_f32 v66, v70, v71
	v_cvt_pk_bf16_f32 v67, v72, v73
	v_cvt_pk_bf16_f32 v68, v74, v75
	v_cvt_pk_bf16_f32 v69, v76, v77
	v_max_f32_e32 v58, 0, v58
	v_max_f32_e32 v59, 0, v59
	global_store_dwordx4 v[82:83], v[66:69], off offset:256
	v_max_f32_e32 v62, v62, v62
	v_max_f32_e32 v63, v63, v63
	v_pk_mul_f32 v[68:69], v[58:59], v[58:59]
	v_max_f32_e32 v59, v60, v60
	v_max_f32_e32 v58, v64, v64
	v_max_f32_e32 v60, 0, v59
	v_max_f32_e32 v59, v65, v65
	v_max_f32_e32 v62, 0, v62
	v_max_f32_e32 v63, 0, v63
	v_max_f32_e32 v58, 0, v58
	v_max_f32_e32 v59, 0, v59
	v_max_f32_e32 v61, 0, v61
	v_pk_mul_f32 v[62:63], v[62:63], v[62:63]
	v_pk_mul_f32 v[64:65], v[58:59], v[58:59]
	v_pk_mul_f32 v[70:71], v[60:61], v[60:61]
	v_lshl_add_u64 v[66:67], v[146:147], 1, s[18:19]
	v_cvt_pk_bf16_f32 v58, v62, v63
	v_cvt_pk_bf16_f32 v59, v64, v65
	v_cvt_pk_bf16_f32 v60, v68, v69
	v_cvt_pk_bf16_f32 v61, v70, v71
	v_max_f32_e32 v50, 0, v50
	v_max_f32_e32 v51, 0, v51
	global_store_dwordx4 v[66:67], v[58:61], off
	v_max_f32_e32 v54, v54, v54
	v_max_f32_e32 v55, v55, v55
	v_pk_mul_f32 v[58:59], v[50:51], v[50:51]
	v_max_f32_e32 v51, v52, v52
	v_max_f32_e32 v50, v56, v56
	v_max_f32_e32 v52, 0, v51
	v_max_f32_e32 v51, v57, v57
	v_max_f32_e32 v54, 0, v54
	v_max_f32_e32 v55, 0, v55
	v_max_f32_e32 v50, 0, v50
	v_max_f32_e32 v51, 0, v51
	v_max_f32_e32 v53, 0, v53
	v_pk_mul_f32 v[54:55], v[54:55], v[54:55]
	v_pk_mul_f32 v[56:57], v[50:51], v[50:51]
	v_pk_mul_f32 v[60:61], v[52:53], v[52:53]
	v_cvt_pk_bf16_f32 v50, v54, v55
	v_cvt_pk_bf16_f32 v51, v56, v57
	v_cvt_pk_bf16_f32 v52, v58, v59
	v_cvt_pk_bf16_f32 v53, v60, v61
	v_max_f32_e32 v42, 0, v42
	v_max_f32_e32 v43, 0, v43
	global_store_dwordx4 v[66:67], v[50:53], off offset:256
	v_max_f32_e32 v46, v46, v46
	v_max_f32_e32 v47, v47, v47
	v_pk_mul_f32 v[52:53], v[42:43], v[42:43]
	v_max_f32_e32 v43, v44, v44
	v_max_f32_e32 v42, v48, v48
	v_max_f32_e32 v44, 0, v43
	v_max_f32_e32 v43, v49, v49
	v_max_f32_e32 v46, 0, v46
	v_max_f32_e32 v47, 0, v47
	v_max_f32_e32 v42, 0, v42
	v_max_f32_e32 v43, 0, v43
	v_max_f32_e32 v45, 0, v45
	v_pk_mul_f32 v[46:47], v[46:47], v[46:47]
	v_pk_mul_f32 v[48:49], v[42:43], v[42:43]
	v_pk_mul_f32 v[54:55], v[44:45], v[44:45]
	v_lshl_add_u64 v[50:51], v[148:149], 1, s[18:19]
	v_cvt_pk_bf16_f32 v42, v46, v47
	v_cvt_pk_bf16_f32 v43, v48, v49
	v_cvt_pk_bf16_f32 v44, v52, v53
	v_cvt_pk_bf16_f32 v45, v54, v55
	v_max_f32_e32 v34, 0, v34
	v_max_f32_e32 v35, 0, v35
	global_store_dwordx4 v[50:51], v[42:45], off
	v_max_f32_e32 v38, v38, v38
	v_max_f32_e32 v39, v39, v39
	v_pk_mul_f32 v[42:43], v[34:35], v[34:35]
	v_max_f32_e32 v35, v36, v36
	v_max_f32_e32 v34, v40, v40
	v_max_f32_e32 v36, 0, v35
	v_max_f32_e32 v35, v41, v41
	v_max_f32_e32 v38, 0, v38
	v_max_f32_e32 v39, 0, v39
	v_max_f32_e32 v34, 0, v34
	v_max_f32_e32 v35, 0, v35
	v_max_f32_e32 v37, 0, v37
	v_pk_mul_f32 v[38:39], v[38:39], v[38:39]
	v_pk_mul_f32 v[40:41], v[34:35], v[34:35]
	v_pk_mul_f32 v[44:45], v[36:37], v[36:37]
	v_cvt_pk_bf16_f32 v34, v38, v39
	v_cvt_pk_bf16_f32 v35, v40, v41
	v_cvt_pk_bf16_f32 v36, v42, v43
	v_cvt_pk_bf16_f32 v37, v44, v45
	v_max_f32_e32 v26, 0, v26
	v_max_f32_e32 v27, 0, v27
	global_store_dwordx4 v[50:51], v[34:37], off offset:256
	v_max_f32_e32 v30, v30, v30
	v_max_f32_e32 v31, v31, v31
	v_pk_mul_f32 v[36:37], v[26:27], v[26:27]
	v_max_f32_e32 v27, v28, v28
	v_max_f32_e32 v26, v32, v32
	v_max_f32_e32 v28, 0, v27
	v_max_f32_e32 v27, v33, v33
	v_max_f32_e32 v30, 0, v30
	v_max_f32_e32 v31, 0, v31
	v_max_f32_e32 v26, 0, v26
	v_max_f32_e32 v27, 0, v27
	v_max_f32_e32 v29, 0, v29
	v_pk_mul_f32 v[30:31], v[30:31], v[30:31]
	v_pk_mul_f32 v[32:33], v[26:27], v[26:27]
	v_pk_mul_f32 v[38:39], v[28:29], v[28:29]
	v_lshl_add_u64 v[34:35], v[150:151], 1, s[18:19]
	v_cvt_pk_bf16_f32 v26, v30, v31
	v_cvt_pk_bf16_f32 v27, v32, v33
	v_cvt_pk_bf16_f32 v28, v36, v37
	v_cvt_pk_bf16_f32 v29, v38, v39
	v_max_f32_e32 v18, 0, v18
	v_max_f32_e32 v19, 0, v19
	global_store_dwordx4 v[34:35], v[26:29], off
	v_max_f32_e32 v22, v22, v22
	v_max_f32_e32 v23, v23, v23
	v_pk_mul_f32 v[26:27], v[18:19], v[18:19]
	v_max_f32_e32 v19, v20, v20
	v_max_f32_e32 v18, v24, v24
	v_max_f32_e32 v20, 0, v19
	v_max_f32_e32 v19, v25, v25
	v_max_f32_e32 v22, 0, v22
	v_max_f32_e32 v23, 0, v23
	v_max_f32_e32 v18, 0, v18
	v_max_f32_e32 v19, 0, v19
	v_max_f32_e32 v21, 0, v21
	v_pk_mul_f32 v[22:23], v[22:23], v[22:23]
	v_pk_mul_f32 v[24:25], v[18:19], v[18:19]
	v_pk_mul_f32 v[28:29], v[20:21], v[20:21]
	v_cvt_pk_bf16_f32 v18, v22, v23
	v_cvt_pk_bf16_f32 v19, v24, v25
	v_cvt_pk_bf16_f32 v20, v26, v27
	v_cvt_pk_bf16_f32 v21, v28, v29
	v_max_f32_e32 v10, 0, v10
	v_max_f32_e32 v11, 0, v11
	global_store_dwordx4 v[34:35], v[18:21], off offset:256
	v_max_f32_e32 v14, v14, v14
	v_max_f32_e32 v15, v15, v15
	v_pk_mul_f32 v[20:21], v[10:11], v[10:11]
	v_max_f32_e32 v11, v12, v12
	v_max_f32_e32 v10, v16, v16
	v_max_f32_e32 v12, 0, v11
	v_max_f32_e32 v11, v17, v17
	v_max_f32_e32 v14, 0, v14
	v_max_f32_e32 v15, 0, v15
	v_max_f32_e32 v10, 0, v10
	v_max_f32_e32 v11, 0, v11
	v_max_f32_e32 v13, 0, v13
	v_pk_mul_f32 v[14:15], v[14:15], v[14:15]
	v_pk_mul_f32 v[16:17], v[10:11], v[10:11]
	v_pk_mul_f32 v[22:23], v[12:13], v[12:13]
	v_lshl_add_u64 v[18:19], v[152:153], 1, s[18:19]
	v_cvt_pk_bf16_f32 v10, v14, v15
	v_cvt_pk_bf16_f32 v11, v16, v17
	v_cvt_pk_bf16_f32 v12, v20, v21
	v_cvt_pk_bf16_f32 v13, v22, v23
	v_max_f32_e32 v2, 0, v2
	v_max_f32_e32 v3, 0, v3
	global_store_dwordx4 v[18:19], v[10:13], off
	v_max_f32_e32 v6, v6, v6
	v_max_f32_e32 v7, v7, v7
	v_pk_mul_f32 v[10:11], v[2:3], v[2:3]
	v_max_f32_e32 v3, v4, v4
	v_max_f32_e32 v2, v8, v8
	v_max_f32_e32 v4, 0, v3
	v_max_f32_e32 v3, v9, v9
	v_max_f32_e32 v6, 0, v6
	v_max_f32_e32 v7, 0, v7
	v_max_f32_e32 v2, 0, v2
	v_max_f32_e32 v3, 0, v3
	v_max_f32_e32 v5, 0, v5
	v_pk_mul_f32 v[6:7], v[6:7], v[6:7]
	v_pk_mul_f32 v[8:9], v[2:3], v[2:3]
	v_pk_mul_f32 v[12:13], v[4:5], v[4:5]
	v_cvt_pk_bf16_f32 v2, v6, v7
	v_cvt_pk_bf16_f32 v3, v8, v9
	v_cvt_pk_bf16_f32 v4, v10, v11
	v_cvt_pk_bf16_f32 v5, v12, v13
	s_and_b64 vcc, exec, s[0:1]
	s_mov_b32 s51, s30
	s_mov_b32 s52, s38
	s_mov_b64 s[20:21], s[80:81]
	s_mov_b64 s[18:19], s[42:43]
	global_store_dwordx4 v[18:19], v[2:5], off offset:256
	s_cbranch_vccz .LBB0_742
	s_waitcnt vmcnt(0)
	v_readlane_b32 s38, v255, 28
	s_cmpk_gt_u32 s26, 0xff
	v_readlane_b32 s39, v255, 29
	v_readlane_b32 s42, v255, 32
	s_cbranch_scc1 .LBB0_753
	s_barrier

.LBB0_819:
	s_lshl_b32 s30, s25, 8
	s_add_i32 s1, s30, s46
	s_lshl_b32 s0, s10, 5
	v_or_b32_e32 v130, s1, v138
	s_lshl_b32 s1, s80, 8
	v_lshrrev_b32_e32 v131, 1, v166
	s_or_b32 s0, s1, s0
	v_and_or_b32 v164, v131, 24, s0
	v_ashrrev_i32_e32 v165, 31, v164
	v_ashrrev_i32_e32 v131, 31, v130
	v_lshl_add_u64 v[162:163], v[164:165], 1, s[34:35]
	v_lshlrev_b64 v[132:133], 12, v[130:131]
	v_lshl_add_u64 v[146:147], v[162:163], 0, v[132:133]
	v_or_b32_e32 v132, 16, v130
	v_ashrrev_i32_e32 v133, 31, v132
	v_lshlrev_b64 v[132:133], 12, v[132:133]
	v_lshl_add_u64 v[132:133], v[162:163], 0, v[132:133]
	s_barrier
	global_load_dwordx4 v[148:151], v[146:147], off
	global_load_dwordx4 v[152:155], v[146:147], off offset:256
	global_load_dwordx4 v[156:159], v[132:133], off
	global_load_dwordx4 v[170:173], v[132:133], off offset:256
	v_or_b32_e32 v132, 32, v130
	v_or_b32_e32 v130, 48, v130
	v_ashrrev_i32_e32 v133, 31, v132
	v_ashrrev_i32_e32 v131, 31, v130
	v_lshlrev_b64 v[132:133], 12, v[132:133]
	v_lshlrev_b64 v[130:131], 12, v[130:131]
	v_lshl_add_u64 v[132:133], v[162:163], 0, v[132:133]
	v_lshl_add_u64 v[130:131], v[162:163], 0, v[130:131]
	global_load_dwordx4 v[142:145], v[132:133], off
	global_load_dwordx4 v[138:141], v[132:133], off offset:256
	global_load_dwordx4 v[134:137], v[130:131], off
	s_nop 0
	global_load_dwordx4 v[130:133], v[130:131], off offset:256
	s_mov_b32 s18, 0x3fd744fd
	s_mov_b64 s[0:1], 0x80000
	v_and_b32_e32 v169, 64, v219
	v_xor_b32_e32 v167, 16, v219
	v_add_u32_e32 v169, 64, v169
	v_and_b32_e32 v168, 63, v166
	s_movk_i32 s95, 0x2000
	s_waitcnt vmcnt(0)
	s_nop 0
	v_lshlrev_b32_e32 v160, 16, v148
	v_and_b32_e32 v161, 0xffff0000, v148
	v_lshlrev_b32_e32 v148, 16, v149
	v_and_b32_e32 v149, 0xffff0000, v149
	v_pk_fma_f32 v[88:89], v[148:149], s[18:19], v[88:89] op_sel_hi:[1,0,1]
	v_lshlrev_b32_e32 v148, 16, v150
	v_and_b32_e32 v149, 0xffff0000, v150
	v_pk_fma_f32 v[94:95], v[148:149], s[18:19], v[94:95] op_sel_hi:[1,0,1]
	v_lshlrev_b32_e32 v148, 16, v152
	v_and_b32_e32 v149, 0xffff0000, v152
	v_pk_fma_f32 v[2:3], v[148:149], s[18:19], v[2:3] op_sel_hi:[1,0,1]
	v_lshlrev_b32_e32 v148, 16, v154
	v_and_b32_e32 v149, 0xffff0000, v154
	v_pk_fma_f32 v[6:7], v[148:149], s[18:19], v[6:7] op_sel_hi:[1,0,1]
	v_lshlrev_b32_e32 v148, 16, v156
	v_and_b32_e32 v149, 0xffff0000, v156
	v_pk_fma_f32 v[98:99], v[148:149], s[18:19], v[98:99] op_sel_hi:[1,0,1]
	v_lshlrev_b32_e32 v148, 16, v158
	v_and_b32_e32 v149, 0xffff0000, v158
	v_pk_fma_f32 v[102:103], v[148:149], s[18:19], v[102:103] op_sel_hi:[1,0,1]
	v_lshlrev_b32_e32 v148, 16, v170
	v_and_b32_e32 v149, 0xffff0000, v170
	v_pk_fma_f32 v[10:11], v[148:149], s[18:19], v[10:11] op_sel_hi:[1,0,1]
	v_lshlrev_b32_e32 v148, 16, v172
	v_and_b32_e32 v149, 0xffff0000, v172
	v_pk_fma_f32 v[14:15], v[148:149], s[18:19], v[14:15] op_sel_hi:[1,0,1]
	v_lshlrev_b32_e32 v148, 16, v142
	v_and_b32_e32 v149, 0xffff0000, v142
	v_lshlrev_b32_e32 v142, 16, v143
	v_and_b32_e32 v143, 0xffff0000, v143
	v_pk_fma_f32 v[116:117], v[142:143], s[18:19], v[116:117] op_sel_hi:[1,0,1]
	v_lshlrev_b32_e32 v142, 16, v144
	v_and_b32_e32 v143, 0xffff0000, v144
	v_pk_fma_f32 v[122:123], v[142:143], s[18:19], v[122:123] op_sel_hi:[1,0,1]
	v_lshlrev_b32_e32 v142, 16, v138
	v_and_b32_e32 v143, 0xffff0000, v138
	v_lshlrev_b32_e32 v138, 16, v139
	v_and_b32_e32 v139, 0xffff0000, v139
	v_pk_fma_f32 v[24:25], v[138:139], s[18:19], v[24:25] op_sel_hi:[1,0,1]
	v_lshlrev_b32_e32 v138, 16, v140
	v_and_b32_e32 v139, 0xffff0000, v140
	v_lshlrev_b32_e32 v150, 16, v151
	v_and_b32_e32 v151, 0xffff0000, v151
	v_pk_fma_f32 v[18:19], v[138:139], s[18:19], v[18:19] op_sel_hi:[1,0,1]
	v_lshlrev_b32_e32 v138, 16, v134
	v_and_b32_e32 v139, 0xffff0000, v134
	v_lshlrev_b32_e32 v134, 16, v135
	v_and_b32_e32 v135, 0xffff0000, v135
	v_pk_fma_f32 v[96:97], v[150:151], s[18:19], v[96:97] op_sel_hi:[1,0,1]
	v_lshlrev_b32_e32 v150, 16, v153
	v_and_b32_e32 v151, 0xffff0000, v153
	v_pk_fma_f32 v[128:129], v[134:135], s[18:19], v[128:129] op_sel_hi:[1,0,1]
	v_lshlrev_b32_e32 v134, 16, v136
	v_and_b32_e32 v135, 0xffff0000, v136
	v_pk_fma_f32 v[4:5], v[150:151], s[18:19], v[4:5] op_sel_hi:[1,0,1]
	v_lshlrev_b32_e32 v150, 16, v155
	v_and_b32_e32 v151, 0xffff0000, v155
	v_pk_fma_f32 v[118:119], v[134:135], s[18:19], v[118:119] op_sel_hi:[1,0,1]
	v_lshlrev_b32_e32 v134, 16, v130
	v_and_b32_e32 v135, 0xffff0000, v130
	v_lshlrev_b32_e32 v130, 16, v131
	v_and_b32_e32 v131, 0xffff0000, v131
	v_pk_fma_f32 v[8:9], v[150:151], s[18:19], v[8:9] op_sel_hi:[1,0,1]
	v_lshlrev_b32_e32 v150, 16, v157
	v_and_b32_e32 v151, 0xffff0000, v157
	v_pk_fma_f32 v[32:33], v[130:131], s[18:19], v[32:33] op_sel_hi:[1,0,1]
	v_pk_fma_f32 v[30:31], v[134:135], s[18:19], v[30:31] op_sel_hi:[1,0,1]
	v_lshlrev_b32_e32 v130, 16, v132
	v_and_b32_e32 v131, 0xffff0000, v132
	v_lshl_add_u64 v[134:135], v[146:147], 0, s[0:1]
	s_mov_b32 s0, 0x80000
	v_pk_fma_f32 v[100:101], v[150:151], s[18:19], v[100:101] op_sel_hi:[1,0,1]
	v_lshlrev_b32_e32 v150, 16, v159
	v_and_b32_e32 v151, 0xffff0000, v159
	v_pk_fma_f32 v[26:27], v[130:131], s[18:19], v[26:27] op_sel_hi:[1,0,1]
	v_add_co_u32_e32 v130, vcc, s0, v146
	s_mov_b64 s[0:1], 0x90000
	v_pk_fma_f32 v[104:105], v[150:151], s[18:19], v[104:105] op_sel_hi:[1,0,1]
	v_lshlrev_b32_e32 v150, 16, v171
	v_and_b32_e32 v151, 0xffff0000, v171
	v_pk_fma_f32 v[22:23], v[142:143], s[18:19], v[22:23] op_sel_hi:[1,0,1]
	v_addc_co_u32_e32 v131, vcc, 0, v147, vcc
	v_lshl_add_u64 v[142:143], v[146:147], 0, s[0:1]
	s_mov_b32 s0, 0x90000
	v_pk_fma_f32 v[12:13], v[150:151], s[18:19], v[12:13] op_sel_hi:[1,0,1]
	v_lshlrev_b32_e32 v150, 16, v173
	v_and_b32_e32 v151, 0xffff0000, v173
	v_lshlrev_b32_e32 v144, 16, v145
	v_and_b32_e32 v145, 0xffff0000, v145
	v_lshlrev_b32_e32 v140, 16, v141
	v_and_b32_e32 v141, 0xffff0000, v141
	v_pk_fma_f32 v[126:127], v[138:139], s[18:19], v[126:127] op_sel_hi:[1,0,1]
	v_lshlrev_b32_e32 v136, 16, v137
	v_and_b32_e32 v137, 0xffff0000, v137
	v_lshlrev_b32_e32 v132, 16, v133
	v_and_b32_e32 v133, 0xffff0000, v133
	v_add_co_u32_e32 v138, vcc, s0, v146
	v_pk_fma_f32 v[86:87], v[160:161], s[18:19], v[86:87] op_sel_hi:[1,0,1]
	v_pk_fma_f32 v[16:17], v[150:151], s[18:19], v[16:17] op_sel_hi:[1,0,1]
	v_pk_fma_f32 v[114:115], v[148:149], s[18:19], v[114:115] op_sel_hi:[1,0,1]
	v_pk_fma_f32 v[124:125], v[144:145], s[18:19], v[124:125] op_sel_hi:[1,0,1]
	v_pk_fma_f32 v[20:21], v[140:141], s[18:19], v[20:21] op_sel_hi:[1,0,1]
	v_pk_fma_f32 v[120:121], v[136:137], s[18:19], v[120:121] op_sel_hi:[1,0,1]
	v_pk_fma_f32 v[28:29], v[132:133], s[18:19], v[28:29] op_sel_hi:[1,0,1]
	v_addc_co_u32_e32 v139, vcc, 0, v147, vcc
	s_mov_b64 s[0:1], 0xa0000
	global_load_dwordx4 v[130:133], v[130:131], off
	s_nop 0
	global_load_dwordx4 v[134:137], v[134:135], off offset:256
	s_nop 0
	global_load_dwordx4 v[138:141], v[138:139], off
	s_nop 0
	global_load_dwordx4 v[154:157], v[142:143], off offset:256
	v_lshl_add_u64 v[142:143], v[146:147], 0, s[0:1]
	s_mov_b32 s0, 0xa0000
	v_add_co_u32_e32 v144, vcc, s0, v146
	s_mov_b64 s[0:1], 0xb0000
	s_nop 0
	v_addc_co_u32_e32 v145, vcc, 0, v147, vcc
	global_load_dwordx4 v[158:161], v[144:145], off
	global_load_dwordx4 v[170:173], v[142:143], off offset:256
	v_lshl_add_u64 v[142:143], v[146:147], 0, s[0:1]
	s_mov_b32 s0, 0xb0000
	v_add_co_u32_e32 v144, vcc, s0, v146
	s_movk_i32 s0, 0x2000
	s_nop 0
	v_addc_co_u32_e32 v145, vcc, 0, v147, vcc
	global_load_dwordx4 v[150:153], v[144:145], off
	global_load_dwordx4 v[146:149], v[142:143], off offset:256
	s_waitcnt vmcnt(0)
	s_nop 0
	v_lshlrev_b32_e32 v142, 16, v130
	v_and_b32_e32 v143, 0xffff0000, v130
	v_lshlrev_b32_e32 v130, 16, v131
	v_and_b32_e32 v131, 0xffff0000, v131
	v_pk_fma_f32 v[112:113], v[130:131], s[18:19], v[112:113] op_sel_hi:[1,0,1]
	v_lshlrev_b32_e32 v130, 16, v132
	v_and_b32_e32 v131, 0xffff0000, v132
	v_lshlrev_b32_e32 v132, 16, v133
	v_and_b32_e32 v133, 0xffff0000, v133
	v_pk_fma_f32 v[130:131], v[130:131], s[18:19], v[106:107] op_sel_hi:[1,0,1]
	v_lshlrev_b32_e32 v106, 16, v134
	v_and_b32_e32 v107, 0xffff0000, v134
	v_pk_fma_f32 v[132:133], v[132:133], s[18:19], v[108:109] op_sel_hi:[1,0,1]
	v_lshlrev_b32_e32 v108, 16, v135
	v_and_b32_e32 v109, 0xffff0000, v135
	v_pk_fma_f32 v[38:39], v[106:107], s[18:19], v[38:39] op_sel_hi:[1,0,1]
	v_lshlrev_b32_e32 v106, 16, v136
	v_and_b32_e32 v107, 0xffff0000, v136
	v_pk_fma_f32 v[40:41], v[108:109], s[18:19], v[40:41] op_sel_hi:[1,0,1]
	v_lshlrev_b32_e32 v108, 16, v137
	v_and_b32_e32 v109, 0xffff0000, v137
	v_pk_fma_f32 v[34:35], v[106:107], s[18:19], v[34:35] op_sel_hi:[1,0,1]
	v_lshlrev_b32_e32 v106, 16, v138
	v_and_b32_e32 v107, 0xffff0000, v138
	v_pk_fma_f32 v[110:111], v[142:143], s[18:19], v[110:111] op_sel_hi:[1,0,1]
	v_pk_fma_f32 v[36:37], v[108:109], s[18:19], v[36:37] op_sel_hi:[1,0,1]
	v_lshlrev_b32_e32 v108, 16, v139
	v_and_b32_e32 v109, 0xffff0000, v139
	v_pk_fma_f32 v[142:143], v[106:107], s[18:19], v[90:91] op_sel_hi:[1,0,1]
	v_lshlrev_b32_e32 v90, 16, v140
	v_and_b32_e32 v91, 0xffff0000, v140
	v_pk_fma_f32 v[144:145], v[108:109], s[18:19], v[92:93] op_sel_hi:[1,0,1]
	v_lshlrev_b32_e32 v92, 16, v141
	v_and_b32_e32 v93, 0xffff0000, v141
	v_pk_fma_f32 v[106:107], v[90:91], s[18:19], v[82:83] op_sel_hi:[1,0,1]
	v_lshlrev_b32_e32 v82, 16, v154
	v_and_b32_e32 v83, 0xffff0000, v154
	v_pk_fma_f32 v[108:109], v[92:93], s[18:19], v[84:85] op_sel_hi:[1,0,1]
	v_lshlrev_b32_e32 v84, 16, v155
	v_and_b32_e32 v85, 0xffff0000, v155
	v_pk_fma_f32 v[46:47], v[82:83], s[18:19], v[46:47] op_sel_hi:[1,0,1]
	v_lshlrev_b32_e32 v82, 16, v156
	v_and_b32_e32 v83, 0xffff0000, v156
	v_pk_fma_f32 v[48:49], v[84:85], s[18:19], v[48:49] op_sel_hi:[1,0,1]
	v_lshlrev_b32_e32 v84, 16, v157
	v_and_b32_e32 v85, 0xffff0000, v157
	v_pk_fma_f32 v[42:43], v[82:83], s[18:19], v[42:43] op_sel_hi:[1,0,1]
	v_lshlrev_b32_e32 v82, 16, v158
	v_and_b32_e32 v83, 0xffff0000, v158
	v_pk_fma_f32 v[44:45], v[84:85], s[18:19], v[44:45] op_sel_hi:[1,0,1]
	v_lshlrev_b32_e32 v84, 16, v159
	v_and_b32_e32 v85, 0xffff0000, v159
	v_pk_fma_f32 v[138:139], v[82:83], s[18:19], v[78:79] op_sel_hi:[1,0,1]
	v_lshlrev_b32_e32 v78, 16, v160
	v_and_b32_e32 v79, 0xffff0000, v160
	v_pk_fma_f32 v[140:141], v[84:85], s[18:19], v[80:81] op_sel_hi:[1,0,1]
	v_lshlrev_b32_e32 v80, 16, v161
	v_and_b32_e32 v81, 0xffff0000, v161
	v_pk_fma_f32 v[90:91], v[78:79], s[18:19], v[74:75] op_sel_hi:[1,0,1]
	v_lshlrev_b32_e32 v74, 16, v170
	v_and_b32_e32 v75, 0xffff0000, v170
	v_pk_fma_f32 v[92:93], v[80:81], s[18:19], v[76:77] op_sel_hi:[1,0,1]
	v_lshlrev_b32_e32 v76, 16, v171
	v_and_b32_e32 v77, 0xffff0000, v171
	v_pk_fma_f32 v[54:55], v[74:75], s[18:19], v[54:55] op_sel_hi:[1,0,1]
	v_lshlrev_b32_e32 v74, 16, v172
	v_and_b32_e32 v75, 0xffff0000, v172
	v_pk_fma_f32 v[56:57], v[76:77], s[18:19], v[56:57] op_sel_hi:[1,0,1]
	v_lshlrev_b32_e32 v76, 16, v173
	v_and_b32_e32 v77, 0xffff0000, v173
	v_pk_fma_f32 v[50:51], v[74:75], s[18:19], v[50:51] op_sel_hi:[1,0,1]
	v_lshlrev_b32_e32 v74, 16, v150
	v_and_b32_e32 v75, 0xffff0000, v150
	v_pk_fma_f32 v[52:53], v[76:77], s[18:19], v[52:53] op_sel_hi:[1,0,1]
	v_lshlrev_b32_e32 v76, 16, v151
	v_and_b32_e32 v77, 0xffff0000, v151
	v_pk_fma_f32 v[134:135], v[74:75], s[18:19], v[70:71] op_sel_hi:[1,0,1]
	v_lshlrev_b32_e32 v70, 16, v152
	v_and_b32_e32 v71, 0xffff0000, v152
	v_pk_fma_f32 v[136:137], v[76:77], s[18:19], v[72:73] op_sel_hi:[1,0,1]
	v_lshlrev_b32_e32 v72, 16, v153
	v_and_b32_e32 v73, 0xffff0000, v153
	v_pk_fma_f32 v[82:83], v[70:71], s[18:19], v[66:67] op_sel_hi:[1,0,1]
	v_lshlrev_b32_e32 v66, 16, v146
	v_and_b32_e32 v67, 0xffff0000, v146
	v_pk_fma_f32 v[84:85], v[72:73], s[18:19], v[68:69] op_sel_hi:[1,0,1]
	v_lshlrev_b32_e32 v68, 16, v147
	v_and_b32_e32 v69, 0xffff0000, v147
	v_pk_fma_f32 v[62:63], v[66:67], s[18:19], v[62:63] op_sel_hi:[1,0,1]
	v_lshlrev_b32_e32 v66, 16, v148
	v_and_b32_e32 v67, 0xffff0000, v148
	v_pk_fma_f32 v[64:65], v[68:69], s[18:19], v[64:65] op_sel_hi:[1,0,1]
	v_lshlrev_b32_e32 v68, 16, v149
	v_and_b32_e32 v69, 0xffff0000, v149
	v_pk_fma_f32 v[58:59], v[66:67], s[18:19], v[58:59] op_sel_hi:[1,0,1]
	v_lshlrev_b64 v[66:67], 2, v[164:165]
	v_pk_fma_f32 v[60:61], v[68:69], s[18:19], v[60:61] op_sel_hi:[1,0,1]
	v_lshl_add_u64 v[68:69], s[4:5], 0, v[66:67]
	v_lshl_add_u64 v[70:71], v[68:69], 0, s[40:41]
	v_add_co_u32_e32 v68, vcc, s0, v68
	v_lshl_add_u64 v[66:67], s[6:7], 0, v[66:67]
	s_nop 0
	v_addc_co_u32_e32 v69, vcc, 0, v69, vcc
	v_lshl_add_u64 v[78:79], v[66:67], 0, s[40:41]
	v_add_co_u32_e32 v66, vcc, s0, v66
	s_nop 1
	v_addc_co_u32_e32 v67, vcc, 0, v67, vcc
	global_load_dwordx4 v[154:157], v[68:69], off
	global_load_dwordx4 v[146:149], v[70:71], off offset:16
	global_load_dwordx4 v[158:161], v[66:67], off
	global_load_dwordx4 v[150:153], v[78:79], off offset:16
	s_nop 0
	global_load_dwordx4 v[66:69], v[70:71], off offset:528
	global_load_dwordx4 v[74:77], v[70:71], off offset:512
	s_nop 0
	global_load_dwordx4 v[70:73], v[78:79], off offset:528
	s_nop 0
	global_load_dwordx4 v[78:81], v[78:79], off offset:512
	v_cmp_lt_i32_e32 vcc, v167, v169
	v_xor_b32_e32 v170, 32, v219
	v_mov_b32_e32 v171, v88
	v_cndmask_b32_e32 v167, v219, v167, vcc
	v_cmp_lt_i32_e32 vcc, v170, v169
	v_mov_b32_e32 v172, v86
	v_mov_b32_e32 v173, v89
	v_cndmask_b32_e32 v169, v219, v170, vcc
	v_mov_b32_e32 v170, v87
	v_pk_add_f32 v[170:171], v[170:171], v[172:173]
	v_mov_b32_e32 v172, v95
	v_mov_b32_e32 v173, v96
	v_mov_b32_e32 v174, v94
	v_mov_b32_e32 v175, v97
	v_pk_add_f32 v[172:173], v[172:173], v[174:175]
	v_add_f32_e32 v170, v170, v171
	v_pk_add_f32 v[172:173], v[172:173], v[172:173] op_sel_hi:[0,1]
	v_add_f32_e32 v171, 0, v170
	v_add_f32_e32 v175, v2, v3
	v_add_f32_e32 v177, v4, v5
	v_mov_b32_e32 v174, v6
	v_mov_b32_e32 v176, v7
	v_mov_b32_e32 v172, v8
	v_mov_b32_e32 v170, v9
	v_pk_add_f32 v[174:175], v[174:175], v[176:177]
	v_pk_add_f32 v[170:171], v[172:173], v[170:171]
	v_lshlrev_b32_e32 v167, 2, v167
	v_pk_add_f32 v[170:171], v[174:175], v[170:171]
	v_lshlrev_b32_e32 v169, 2, v169
	v_add_f32_e32 v170, v170, v171
	v_mov_b32_e32 v171, v170
	s_nop 1
	v_permlane16_swap_b32 v171, v170
	s_lshl_b32 s0, s10, 3
	s_add_i32 s0, s0, 0
	v_cmp_gt_u32_e32 vcc, 16, v168
	s_waitcnt lgkmcnt(0)
	v_add_f32_e32 v170, v170, v171
	v_mov_b32_e32 v171, v170
	s_nop 1
	v_permlane32_swap_b32 v171, v170
	s_waitcnt lgkmcnt(0)
	v_add_f32_e32 v171, v170, v171
	v_fmamk_f32 v172, v171, 0xbc800000, v89
	v_fmamk_f32 v174, v171, 0xbc800000, v87
	v_fmamk_f32 v170, v171, 0xbc800000, v88
	v_fmamk_f32 v173, v171, 0xbc800000, v86
	v_mul_f32_e32 v174, v174, v174
	v_mul_f32_e32 v172, v172, v172
	v_fmac_f32_e32 v174, v173, v173
	v_fmac_f32_e32 v172, v170, v170
	v_fmamk_f32 v173, v171, 0xbc800000, v97
	v_fmamk_f32 v175, v171, 0xbc800000, v95
	v_add_f32_e32 v170, v174, v172
	v_fmamk_f32 v172, v171, 0xbc800000, v96
	v_fmamk_f32 v174, v171, 0xbc800000, v94
	v_mul_f32_e32 v175, v175, v175
	v_mul_f32_e32 v173, v173, v173
	v_fmac_f32_e32 v175, v174, v174
	v_fmac_f32_e32 v173, v172, v172
	v_add_f32_e32 v172, v175, v173
	v_fmamk_f32 v173, v171, 0xbc800000, v5
	v_fmamk_f32 v175, v171, 0xbc800000, v3
	v_add_f32_e32 v170, v170, v172
	v_fmamk_f32 v172, v171, 0xbc800000, v4
	v_fmamk_f32 v174, v171, 0xbc800000, v2
	v_mul_f32_e32 v175, v175, v175
	v_mul_f32_e32 v173, v173, v173
	v_fmac_f32_e32 v175, v174, v174
	v_fmac_f32_e32 v173, v172, v172
	v_add_f32_e32 v172, v175, v173
	v_fmamk_f32 v173, v171, 0xbc800000, v9
	v_fmamk_f32 v175, v171, 0xbc800000, v7
	v_add_f32_e32 v170, v172, v170
	v_fmamk_f32 v172, v171, 0xbc800000, v8
	v_fmamk_f32 v174, v171, 0xbc800000, v6
	v_mul_f32_e32 v175, v175, v175
	v_mul_f32_e32 v173, v173, v173
	v_fmac_f32_e32 v175, v174, v174
	v_fmac_f32_e32 v173, v172, v172
	v_add_f32_e32 v172, v175, v173
	v_add_f32_e32 v170, v172, v170
	v_mov_b32_e32 v172, v170
	s_nop 1
	v_permlane16_swap_b32 v172, v170
	s_waitcnt lgkmcnt(0)
	v_add_f32_e32 v172, v170, v172
	v_mov_b32_e32 v173, v172
	s_nop 1
	v_permlane32_swap_b32 v173, v172
	v_lshl_add_u32 v170, v1, 5, s0
	s_and_saveexec_b64 s[0:1], vcc
	v_readlane_b32 s38, v255, 28
	v_readlane_b32 s44, v255, 30
	v_readlane_b32 s39, v255, 29
	v_readlane_b32 s45, v255, 31
	v_readlane_b32 s42, v255, 32
	s_cbranch_execz .LBB0_821
	v_mul_f32_e32 v174, 0x3c800000, v171
	s_waitcnt lgkmcnt(0)
	v_add_f32_e32 v175, v172, v173
	ds_write_b64 v170, v[174:175]
.LBB0_821:
	s_or_b64 exec, exec, s[0:1]
	v_mov_b32_e32 v172, v99
	s_waitcnt lgkmcnt(0)
	v_mov_b32_e32 v173, v100
	v_mov_b32_e32 v174, v98
	v_mov_b32_e32 v175, v101
	v_pk_add_f32 v[172:173], v[172:173], v[174:175]
	v_mov_b32_e32 v174, v103
	v_mov_b32_e32 v175, v104
	v_mov_b32_e32 v176, v102
	v_mov_b32_e32 v177, v105
	v_pk_add_f32 v[174:175], v[174:175], v[176:177]
	v_add_f32_e32 v171, v172, v173
	v_pk_add_f32 v[174:175], v[174:175], v[174:175] op_sel_hi:[0,1]
	v_add_f32_e32 v173, 0, v171
	v_add_f32_e32 v177, v10, v11
	v_add_f32_e32 v179, v12, v13
	v_mov_b32_e32 v176, v14
	v_mov_b32_e32 v178, v15
	v_mov_b32_e32 v174, v16
	v_mov_b32_e32 v172, v17
	v_pk_add_f32 v[176:177], v[176:177], v[178:179]
	v_pk_add_f32 v[172:173], v[174:175], v[172:173]
	s_nop 0
	v_pk_add_f32 v[172:173], v[176:177], v[172:173]
	s_nop 0
	v_add_f32_e32 v171, v172, v173
	v_mov_b32_e32 v172, v171
	s_nop 1
	v_permlane16_swap_b32 v172, v171
	s_waitcnt lgkmcnt(0)
	v_add_f32_e32 v171, v171, v172
	v_mov_b32_e32 v172, v171
	s_nop 1
	v_permlane32_swap_b32 v172, v171
	s_waitcnt lgkmcnt(0)
	v_add_f32_e32 v171, v171, v172
	v_fmamk_f32 v173, v171, 0xbc800000, v101
	v_fmamk_f32 v175, v171, 0xbc800000, v99
	v_fmamk_f32 v172, v171, 0xbc800000, v100
	v_fmamk_f32 v174, v171, 0xbc800000, v98
	v_mul_f32_e32 v175, v175, v175
	v_mul_f32_e32 v173, v173, v173
	v_fmac_f32_e32 v175, v174, v174
	v_fmac_f32_e32 v173, v172, v172
	v_fmamk_f32 v174, v171, 0xbc800000, v105
	v_fmamk_f32 v176, v171, 0xbc800000, v103
	v_add_f32_e32 v172, v175, v173
	v_fmamk_f32 v173, v171, 0xbc800000, v104
	v_fmamk_f32 v175, v171, 0xbc800000, v102
	v_mul_f32_e32 v176, v176, v176
	v_mul_f32_e32 v174, v174, v174
	v_fmac_f32_e32 v176, v175, v175
	v_fmac_f32_e32 v174, v173, v173
	v_add_f32_e32 v173, v176, v174
	v_fmamk_f32 v174, v171, 0xbc800000, v13
	v_fmamk_f32 v176, v171, 0xbc800000, v11
	v_add_f32_e32 v172, v172, v173
	v_fmamk_f32 v173, v171, 0xbc800000, v12
	v_fmamk_f32 v175, v171, 0xbc800000, v10
	v_mul_f32_e32 v176, v176, v176
	v_mul_f32_e32 v174, v174, v174
	v_fmac_f32_e32 v176, v175, v175
	v_fmac_f32_e32 v174, v173, v173
	v_add_f32_e32 v173, v176, v174
	v_fmamk_f32 v174, v171, 0xbc800000, v17
	v_fmamk_f32 v176, v171, 0xbc800000, v15
	v_add_f32_e32 v172, v173, v172
	v_fmamk_f32 v173, v171, 0xbc800000, v16
	v_fmamk_f32 v175, v171, 0xbc800000, v14
	v_mul_f32_e32 v176, v176, v176
	v_mul_f32_e32 v174, v174, v174
	v_fmac_f32_e32 v176, v175, v175
	v_fmac_f32_e32 v174, v173, v173
	v_add_f32_e32 v173, v176, v174
	v_add_f32_e32 v172, v173, v172
	v_mov_b32_e32 v173, v172
	s_nop 1
	v_permlane16_swap_b32 v173, v172
	s_waitcnt lgkmcnt(0)
	v_add_f32_e32 v172, v172, v173
	v_mov_b32_e32 v173, v172
	s_nop 1
	v_permlane32_swap_b32 v173, v172
	s_and_saveexec_b64 s[0:1], vcc
	s_cbranch_execz .LBB0_823
	v_mul_f32_e32 v174, 0x3c800000, v171
	s_waitcnt lgkmcnt(0)
	v_add_f32_e32 v175, v172, v173
	ds_write_b64 v170, v[174:175] offset:512
.LBB0_823:
	s_or_b64 exec, exec, s[0:1]
	v_mov_b32_e32 v172, v115
	s_waitcnt lgkmcnt(0)
	v_mov_b32_e32 v173, v116
	v_mov_b32_e32 v174, v114
	v_mov_b32_e32 v175, v117
	v_pk_add_f32 v[172:173], v[172:173], v[174:175]
	v_mov_b32_e32 v174, v123
	v_mov_b32_e32 v175, v124
	v_mov_b32_e32 v176, v122
	v_mov_b32_e32 v177, v125
	v_pk_add_f32 v[174:175], v[174:175], v[176:177]
	v_add_f32_e32 v171, v172, v173
	v_pk_add_f32 v[174:175], v[174:175], v[174:175] op_sel_hi:[0,1]
	v_add_f32_e32 v173, 0, v171
	v_add_f32_e32 v177, v22, v23
	v_add_f32_e32 v179, v24, v25
	v_mov_b32_e32 v176, v18
	v_mov_b32_e32 v178, v19
	v_mov_b32_e32 v174, v20
	v_mov_b32_e32 v172, v21
	v_pk_add_f32 v[176:177], v[176:177], v[178:179]
	v_pk_add_f32 v[172:173], v[174:175], v[172:173]
	s_nop 0
	v_pk_add_f32 v[172:173], v[176:177], v[172:173]
	s_nop 0
	v_add_f32_e32 v171, v172, v173
	v_mov_b32_e32 v172, v171
	s_nop 1
	v_permlane16_swap_b32 v172, v171
	s_waitcnt lgkmcnt(0)
	v_add_f32_e32 v171, v171, v172
	v_mov_b32_e32 v172, v171
	s_nop 1
	v_permlane32_swap_b32 v172, v171
	s_waitcnt lgkmcnt(0)
	v_add_f32_e32 v171, v171, v172
	v_fmamk_f32 v173, v171, 0xbc800000, v117
	v_fmamk_f32 v175, v171, 0xbc800000, v115
	v_fmamk_f32 v172, v171, 0xbc800000, v116
	v_fmamk_f32 v174, v171, 0xbc800000, v114
	v_mul_f32_e32 v175, v175, v175
	v_mul_f32_e32 v173, v173, v173
	v_fmac_f32_e32 v175, v174, v174
	v_fmac_f32_e32 v173, v172, v172
	v_fmamk_f32 v174, v171, 0xbc800000, v125
	v_fmamk_f32 v176, v171, 0xbc800000, v123
	v_add_f32_e32 v172, v175, v173
	v_fmamk_f32 v173, v171, 0xbc800000, v124
	v_fmamk_f32 v175, v171, 0xbc800000, v122
	v_mul_f32_e32 v176, v176, v176
	v_mul_f32_e32 v174, v174, v174
	v_fmac_f32_e32 v176, v175, v175
	v_fmac_f32_e32 v174, v173, v173
	v_add_f32_e32 v173, v176, v174
	v_fmamk_f32 v174, v171, 0xbc800000, v25
	v_fmamk_f32 v176, v171, 0xbc800000, v23
	v_add_f32_e32 v172, v172, v173
	v_fmamk_f32 v173, v171, 0xbc800000, v24
	v_fmamk_f32 v175, v171, 0xbc800000, v22
	v_mul_f32_e32 v176, v176, v176
	v_mul_f32_e32 v174, v174, v174
	v_fmac_f32_e32 v176, v175, v175
	v_fmac_f32_e32 v174, v173, v173
	v_add_f32_e32 v173, v176, v174
	v_fmamk_f32 v174, v171, 0xbc800000, v21
	v_fmamk_f32 v176, v171, 0xbc800000, v19
	v_add_f32_e32 v172, v173, v172
	v_fmamk_f32 v173, v171, 0xbc800000, v20
	v_fmamk_f32 v175, v171, 0xbc800000, v18
	v_mul_f32_e32 v176, v176, v176
	v_mul_f32_e32 v174, v174, v174
	v_fmac_f32_e32 v176, v175, v175
	v_fmac_f32_e32 v174, v173, v173
	v_add_f32_e32 v173, v176, v174
	v_add_f32_e32 v172, v173, v172
	v_mov_b32_e32 v173, v172
	s_nop 1
	v_permlane16_swap_b32 v173, v172
	s_waitcnt lgkmcnt(0)
	v_add_f32_e32 v172, v172, v173
	v_mov_b32_e32 v173, v172
	s_nop 1
	v_permlane32_swap_b32 v173, v172
	s_and_saveexec_b64 s[0:1], vcc
	s_cbranch_execz .LBB0_825
	v_mul_f32_e32 v174, 0x3c800000, v171
	s_waitcnt lgkmcnt(0)
	v_add_f32_e32 v175, v172, v173
	ds_write_b64 v170, v[174:175] offset:1024
.LBB0_825:
	s_or_b64 exec, exec, s[0:1]
	v_mov_b32_e32 v172, v127
	s_waitcnt lgkmcnt(0)
	v_mov_b32_e32 v173, v128
	v_mov_b32_e32 v174, v126
	v_mov_b32_e32 v175, v129
	v_pk_add_f32 v[172:173], v[172:173], v[174:175]
	v_mov_b32_e32 v174, v119
	v_mov_b32_e32 v175, v120
	v_mov_b32_e32 v176, v118
	v_mov_b32_e32 v177, v121
	v_pk_add_f32 v[174:175], v[174:175], v[176:177]
	v_add_f32_e32 v171, v172, v173
	v_pk_add_f32 v[174:175], v[174:175], v[174:175] op_sel_hi:[0,1]
	v_add_f32_e32 v173, 0, v171
	v_add_f32_e32 v177, v30, v31
	v_add_f32_e32 v179, v32, v33
	v_mov_b32_e32 v176, v26
	v_mov_b32_e32 v178, v27
	v_mov_b32_e32 v174, v28
	v_mov_b32_e32 v172, v29
	v_pk_add_f32 v[176:177], v[176:177], v[178:179]
	v_pk_add_f32 v[172:173], v[174:175], v[172:173]
	s_nop 0
	v_pk_add_f32 v[172:173], v[176:177], v[172:173]
	s_nop 0
	v_add_f32_e32 v171, v172, v173
	v_mov_b32_e32 v172, v171
	s_nop 1
	v_permlane16_swap_b32 v172, v171
	s_waitcnt lgkmcnt(0)
	v_add_f32_e32 v171, v171, v172
	v_mov_b32_e32 v172, v171
	s_nop 1
	v_permlane32_swap_b32 v172, v171
	s_waitcnt lgkmcnt(0)
	v_add_f32_e32 v171, v171, v172
	v_fmamk_f32 v173, v171, 0xbc800000, v129
	v_fmamk_f32 v175, v171, 0xbc800000, v127
	v_fmamk_f32 v172, v171, 0xbc800000, v128
	v_fmamk_f32 v174, v171, 0xbc800000, v126
	v_mul_f32_e32 v175, v175, v175
	v_mul_f32_e32 v173, v173, v173
	v_fmac_f32_e32 v175, v174, v174
	v_fmac_f32_e32 v173, v172, v172
	v_fmamk_f32 v174, v171, 0xbc800000, v121
	v_fmamk_f32 v176, v171, 0xbc800000, v119
	v_add_f32_e32 v172, v175, v173
	v_fmamk_f32 v173, v171, 0xbc800000, v120
	v_fmamk_f32 v175, v171, 0xbc800000, v118
	v_mul_f32_e32 v176, v176, v176
	v_mul_f32_e32 v174, v174, v174
	v_fmac_f32_e32 v176, v175, v175
	v_fmac_f32_e32 v174, v173, v173
	v_add_f32_e32 v173, v176, v174
	v_fmamk_f32 v174, v171, 0xbc800000, v33
	v_fmamk_f32 v176, v171, 0xbc800000, v31
	v_add_f32_e32 v172, v172, v173
	v_fmamk_f32 v173, v171, 0xbc800000, v32
	v_fmamk_f32 v175, v171, 0xbc800000, v30
	v_mul_f32_e32 v176, v176, v176
	v_mul_f32_e32 v174, v174, v174
	v_fmac_f32_e32 v176, v175, v175
	v_fmac_f32_e32 v174, v173, v173
	v_add_f32_e32 v173, v176, v174
	v_fmamk_f32 v174, v171, 0xbc800000, v29
	v_fmamk_f32 v176, v171, 0xbc800000, v27
	v_add_f32_e32 v172, v173, v172
	v_fmamk_f32 v173, v171, 0xbc800000, v28
	v_fmamk_f32 v175, v171, 0xbc800000, v26
	v_mul_f32_e32 v176, v176, v176
	v_mul_f32_e32 v174, v174, v174
	v_fmac_f32_e32 v176, v175, v175
	v_fmac_f32_e32 v174, v173, v173
	v_add_f32_e32 v173, v176, v174
	v_add_f32_e32 v172, v173, v172
	v_mov_b32_e32 v173, v172
	s_nop 1
	v_permlane16_swap_b32 v173, v172
	s_waitcnt lgkmcnt(0)
	v_add_f32_e32 v172, v172, v173
	v_mov_b32_e32 v173, v172
	s_nop 1
	v_permlane32_swap_b32 v173, v172
	s_and_saveexec_b64 s[0:1], vcc
	s_cbranch_execz .LBB0_827
	v_mul_f32_e32 v174, 0x3c800000, v171
	s_waitcnt lgkmcnt(0)
	v_add_f32_e32 v175, v172, v173
	ds_write_b64 v170, v[174:175] offset:1536
.LBB0_827:
	s_or_b64 exec, exec, s[0:1]
	v_mov_b32_e32 v172, v111
	s_waitcnt lgkmcnt(0)
	v_mov_b32_e32 v173, v112
	v_mov_b32_e32 v174, v110
	v_mov_b32_e32 v175, v113
	v_pk_add_f32 v[172:173], v[172:173], v[174:175]
	v_mov_b32_e32 v174, v131
	v_mov_b32_e32 v175, v132
	v_mov_b32_e32 v176, v130
	v_mov_b32_e32 v177, v133
	v_pk_add_f32 v[174:175], v[174:175], v[176:177]
	v_add_f32_e32 v171, v172, v173
	v_pk_add_f32 v[174:175], v[174:175], v[174:175] op_sel_hi:[0,1]
	v_add_f32_e32 v173, 0, v171
	v_add_f32_e32 v177, v38, v39
	v_add_f32_e32 v179, v40, v41
	v_mov_b32_e32 v176, v34
	v_mov_b32_e32 v178, v35
	v_mov_b32_e32 v174, v36
	v_mov_b32_e32 v172, v37
	v_pk_add_f32 v[176:177], v[176:177], v[178:179]
	v_pk_add_f32 v[172:173], v[174:175], v[172:173]
	s_nop 0
	v_pk_add_f32 v[172:173], v[176:177], v[172:173]
	s_nop 0
	v_add_f32_e32 v171, v172, v173
	v_mov_b32_e32 v172, v171
	s_nop 1
	v_permlane16_swap_b32 v172, v171
	s_waitcnt lgkmcnt(0)
	v_add_f32_e32 v171, v171, v172
	v_mov_b32_e32 v172, v171
	s_nop 1
	v_permlane32_swap_b32 v172, v171
	s_waitcnt lgkmcnt(0)
	v_add_f32_e32 v171, v171, v172
	v_fmamk_f32 v173, v171, 0xbc800000, v113
	v_fmamk_f32 v175, v171, 0xbc800000, v111
	v_fmamk_f32 v172, v171, 0xbc800000, v112
	v_fmamk_f32 v174, v171, 0xbc800000, v110
	v_mul_f32_e32 v175, v175, v175
	v_mul_f32_e32 v173, v173, v173
	v_fmac_f32_e32 v175, v174, v174
	v_fmac_f32_e32 v173, v172, v172
	v_fmamk_f32 v174, v171, 0xbc800000, v133
	v_fmamk_f32 v176, v171, 0xbc800000, v131
	v_add_f32_e32 v172, v175, v173
	v_fmamk_f32 v173, v171, 0xbc800000, v132
	v_fmamk_f32 v175, v171, 0xbc800000, v130
	v_mul_f32_e32 v176, v176, v176
	v_mul_f32_e32 v174, v174, v174
	v_fmac_f32_e32 v176, v175, v175
	v_fmac_f32_e32 v174, v173, v173
	v_add_f32_e32 v173, v176, v174
	v_fmamk_f32 v174, v171, 0xbc800000, v41
	v_fmamk_f32 v176, v171, 0xbc800000, v39
	v_add_f32_e32 v172, v172, v173
	v_fmamk_f32 v173, v171, 0xbc800000, v40
	v_fmamk_f32 v175, v171, 0xbc800000, v38
	v_mul_f32_e32 v176, v176, v176
	v_mul_f32_e32 v174, v174, v174
	v_fmac_f32_e32 v176, v175, v175
	v_fmac_f32_e32 v174, v173, v173
	v_add_f32_e32 v173, v176, v174
	v_fmamk_f32 v174, v171, 0xbc800000, v37
	v_fmamk_f32 v176, v171, 0xbc800000, v35
	v_add_f32_e32 v172, v173, v172
	v_fmamk_f32 v173, v171, 0xbc800000, v36
	v_fmamk_f32 v175, v171, 0xbc800000, v34
	v_mul_f32_e32 v176, v176, v176
	v_mul_f32_e32 v174, v174, v174
	v_fmac_f32_e32 v176, v175, v175
	v_fmac_f32_e32 v174, v173, v173
	v_add_f32_e32 v173, v176, v174
	v_add_f32_e32 v172, v173, v172
	v_mov_b32_e32 v173, v172
	s_nop 1
	v_permlane16_swap_b32 v173, v172
	s_waitcnt lgkmcnt(0)
	v_add_f32_e32 v172, v172, v173
	v_mov_b32_e32 v173, v172
	s_nop 1
	v_permlane32_swap_b32 v173, v172
	s_and_saveexec_b64 s[0:1], vcc
	s_cbranch_execz .LBB0_829
	v_mul_f32_e32 v174, 0x3c800000, v171
	s_waitcnt lgkmcnt(0)
	v_add_f32_e32 v175, v172, v173
	ds_write_b64 v170, v[174:175] offset:4096
.LBB0_829:
	s_or_b64 exec, exec, s[0:1]
	v_mov_b32_e32 v172, v143
	s_waitcnt lgkmcnt(0)
	v_mov_b32_e32 v173, v144
	v_mov_b32_e32 v174, v142
	v_mov_b32_e32 v175, v145
	v_pk_add_f32 v[172:173], v[172:173], v[174:175]
	v_mov_b32_e32 v174, v107
	v_mov_b32_e32 v175, v108
	v_mov_b32_e32 v176, v106
	v_mov_b32_e32 v177, v109
	v_pk_add_f32 v[174:175], v[174:175], v[176:177]
	v_add_f32_e32 v171, v172, v173
	v_pk_add_f32 v[174:175], v[174:175], v[174:175] op_sel_hi:[0,1]
	v_add_f32_e32 v173, 0, v171
	v_add_f32_e32 v177, v46, v47
	v_add_f32_e32 v179, v48, v49
	v_mov_b32_e32 v176, v42
	v_mov_b32_e32 v178, v43
	v_mov_b32_e32 v174, v44
	v_mov_b32_e32 v172, v45
	v_pk_add_f32 v[176:177], v[176:177], v[178:179]
	v_pk_add_f32 v[172:173], v[174:175], v[172:173]
	s_nop 0
	v_pk_add_f32 v[172:173], v[176:177], v[172:173]
	s_nop 0
	v_add_f32_e32 v171, v172, v173
	v_mov_b32_e32 v172, v171
	s_nop 1
	v_permlane16_swap_b32 v172, v171
	s_waitcnt lgkmcnt(0)
	v_add_f32_e32 v171, v171, v172
	v_mov_b32_e32 v172, v171
	s_nop 1
	v_permlane32_swap_b32 v172, v171
	s_waitcnt lgkmcnt(0)
	v_add_f32_e32 v171, v171, v172
	v_fmamk_f32 v173, v171, 0xbc800000, v145
	v_fmamk_f32 v175, v171, 0xbc800000, v143
	v_fmamk_f32 v172, v171, 0xbc800000, v144
	v_fmamk_f32 v174, v171, 0xbc800000, v142
	v_mul_f32_e32 v175, v175, v175
	v_mul_f32_e32 v173, v173, v173
	v_fmac_f32_e32 v175, v174, v174
	v_fmac_f32_e32 v173, v172, v172
	v_fmamk_f32 v174, v171, 0xbc800000, v109
	v_fmamk_f32 v176, v171, 0xbc800000, v107
	v_add_f32_e32 v172, v175, v173
	v_fmamk_f32 v173, v171, 0xbc800000, v108
	v_fmamk_f32 v175, v171, 0xbc800000, v106
	v_mul_f32_e32 v176, v176, v176
	v_mul_f32_e32 v174, v174, v174
	v_fmac_f32_e32 v176, v175, v175
	v_fmac_f32_e32 v174, v173, v173
	v_add_f32_e32 v173, v176, v174
	v_fmamk_f32 v174, v171, 0xbc800000, v49
	v_fmamk_f32 v176, v171, 0xbc800000, v47
	v_add_f32_e32 v172, v172, v173
	v_fmamk_f32 v173, v171, 0xbc800000, v48
	v_fmamk_f32 v175, v171, 0xbc800000, v46
	v_mul_f32_e32 v176, v176, v176
	v_mul_f32_e32 v174, v174, v174
	v_fmac_f32_e32 v176, v175, v175
	v_fmac_f32_e32 v174, v173, v173
	v_add_f32_e32 v173, v176, v174
	v_fmamk_f32 v174, v171, 0xbc800000, v45
	v_fmamk_f32 v176, v171, 0xbc800000, v43
	v_add_f32_e32 v172, v173, v172
	v_fmamk_f32 v173, v171, 0xbc800000, v44
	v_fmamk_f32 v175, v171, 0xbc800000, v42
	v_mul_f32_e32 v176, v176, v176
	v_mul_f32_e32 v174, v174, v174
	v_fmac_f32_e32 v176, v175, v175
	v_fmac_f32_e32 v174, v173, v173
	v_add_f32_e32 v173, v176, v174
	v_add_f32_e32 v172, v173, v172
	v_mov_b32_e32 v173, v172
	s_nop 1
	v_permlane16_swap_b32 v173, v172
	s_waitcnt lgkmcnt(0)
	v_add_f32_e32 v172, v172, v173
	v_mov_b32_e32 v173, v172
	s_nop 1
	v_permlane32_swap_b32 v173, v172
	s_and_saveexec_b64 s[0:1], vcc
	s_cbranch_execz .LBB0_831
	v_mul_f32_e32 v174, 0x3c800000, v171
	s_waitcnt lgkmcnt(0)
	v_add_f32_e32 v175, v172, v173
	ds_write_b64 v170, v[174:175] offset:4608
.LBB0_831:
	s_or_b64 exec, exec, s[0:1]
	v_mov_b32_e32 v172, v139
	s_waitcnt lgkmcnt(0)
	v_mov_b32_e32 v173, v140
	v_mov_b32_e32 v174, v138
	v_mov_b32_e32 v175, v141
	v_pk_add_f32 v[172:173], v[172:173], v[174:175]
	v_mov_b32_e32 v174, v91
	v_mov_b32_e32 v175, v92
	v_mov_b32_e32 v176, v90
	v_mov_b32_e32 v177, v93
	v_pk_add_f32 v[174:175], v[174:175], v[176:177]
	v_add_f32_e32 v171, v172, v173
	v_pk_add_f32 v[174:175], v[174:175], v[174:175] op_sel_hi:[0,1]
	v_add_f32_e32 v173, 0, v171
	v_add_f32_e32 v177, v54, v55
	v_add_f32_e32 v179, v56, v57
	v_mov_b32_e32 v176, v50
	v_mov_b32_e32 v178, v51
	v_mov_b32_e32 v174, v52
	v_mov_b32_e32 v172, v53
	v_pk_add_f32 v[176:177], v[176:177], v[178:179]
	v_pk_add_f32 v[172:173], v[174:175], v[172:173]
	s_nop 0
	v_pk_add_f32 v[172:173], v[176:177], v[172:173]
	s_nop 0
	v_add_f32_e32 v171, v172, v173
	v_mov_b32_e32 v172, v171
	s_nop 1
	v_permlane16_swap_b32 v172, v171
	s_waitcnt lgkmcnt(0)
	v_add_f32_e32 v171, v171, v172
	v_mov_b32_e32 v172, v171
	s_nop 1
	v_permlane32_swap_b32 v172, v171
	s_waitcnt lgkmcnt(0)
	v_add_f32_e32 v171, v171, v172
	v_fmamk_f32 v173, v171, 0xbc800000, v141
	v_fmamk_f32 v175, v171, 0xbc800000, v139
	v_fmamk_f32 v172, v171, 0xbc800000, v140
	v_fmamk_f32 v174, v171, 0xbc800000, v138
	v_mul_f32_e32 v175, v175, v175
	v_mul_f32_e32 v173, v173, v173
	v_fmac_f32_e32 v175, v174, v174
	v_fmac_f32_e32 v173, v172, v172
	v_fmamk_f32 v174, v171, 0xbc800000, v93
	v_fmamk_f32 v176, v171, 0xbc800000, v91
	v_add_f32_e32 v172, v175, v173
	v_fmamk_f32 v173, v171, 0xbc800000, v92
	v_fmamk_f32 v175, v171, 0xbc800000, v90
	v_mul_f32_e32 v176, v176, v176
	v_mul_f32_e32 v174, v174, v174
	v_fmac_f32_e32 v176, v175, v175
	v_fmac_f32_e32 v174, v173, v173
	v_add_f32_e32 v173, v176, v174
	v_fmamk_f32 v174, v171, 0xbc800000, v57
	v_fmamk_f32 v176, v171, 0xbc800000, v55
	v_add_f32_e32 v172, v172, v173
	v_fmamk_f32 v173, v171, 0xbc800000, v56
	v_fmamk_f32 v175, v171, 0xbc800000, v54
	v_mul_f32_e32 v176, v176, v176
	v_mul_f32_e32 v174, v174, v174
	v_fmac_f32_e32 v176, v175, v175
	v_fmac_f32_e32 v174, v173, v173
	v_add_f32_e32 v173, v176, v174
	v_fmamk_f32 v174, v171, 0xbc800000, v53
	v_fmamk_f32 v176, v171, 0xbc800000, v51
	v_add_f32_e32 v172, v173, v172
	v_fmamk_f32 v173, v171, 0xbc800000, v52
	v_fmamk_f32 v175, v171, 0xbc800000, v50
	v_mul_f32_e32 v176, v176, v176
	v_mul_f32_e32 v174, v174, v174
	v_fmac_f32_e32 v176, v175, v175
	v_fmac_f32_e32 v174, v173, v173
	v_add_f32_e32 v173, v176, v174
	v_add_f32_e32 v172, v173, v172
	v_mov_b32_e32 v173, v172
	s_nop 1
	v_permlane16_swap_b32 v173, v172
	s_waitcnt lgkmcnt(0)
	v_add_f32_e32 v172, v172, v173
	v_mov_b32_e32 v173, v172
	s_nop 1
	v_permlane32_swap_b32 v173, v172
	s_and_saveexec_b64 s[0:1], vcc
	s_cbranch_execz .LBB0_833
	v_mul_f32_e32 v174, 0x3c800000, v171
	s_waitcnt lgkmcnt(0)
	v_add_f32_e32 v175, v172, v173
	ds_write_b64 v170, v[174:175] offset:5120
.LBB0_833:
	s_or_b64 exec, exec, s[0:1]
	v_mov_b32_e32 v172, v135
	s_waitcnt lgkmcnt(0)
	v_mov_b32_e32 v173, v136
	v_mov_b32_e32 v174, v134
	v_mov_b32_e32 v175, v137
	v_pk_add_f32 v[172:173], v[172:173], v[174:175]
	v_mov_b32_e32 v174, v83
	v_mov_b32_e32 v175, v84
	v_mov_b32_e32 v176, v82
	v_mov_b32_e32 v177, v85
	v_pk_add_f32 v[174:175], v[174:175], v[176:177]
	v_add_f32_e32 v171, v172, v173
	v_pk_add_f32 v[174:175], v[174:175], v[174:175] op_sel_hi:[0,1]
	v_add_f32_e32 v173, 0, v171
	v_add_f32_e32 v177, v62, v63
	v_add_f32_e32 v179, v64, v65
	v_mov_b32_e32 v176, v58
	v_mov_b32_e32 v178, v59
	v_mov_b32_e32 v174, v60
	v_mov_b32_e32 v172, v61
	v_pk_add_f32 v[176:177], v[176:177], v[178:179]
	v_pk_add_f32 v[172:173], v[174:175], v[172:173]
	s_nop 0
	v_pk_add_f32 v[172:173], v[176:177], v[172:173]
	s_nop 0
	v_add_f32_e32 v171, v172, v173
	v_mov_b32_e32 v172, v171
	s_nop 1
	v_permlane16_swap_b32 v172, v171
	s_waitcnt lgkmcnt(0)
	v_add_f32_e32 v171, v171, v172
	v_mov_b32_e32 v172, v171
	s_nop 1
	v_permlane32_swap_b32 v172, v171
	s_waitcnt lgkmcnt(0)
	v_add_f32_e32 v171, v171, v172
	v_fmamk_f32 v173, v171, 0xbc800000, v137
	v_fmamk_f32 v175, v171, 0xbc800000, v135
	v_fmamk_f32 v172, v171, 0xbc800000, v136
	v_fmamk_f32 v174, v171, 0xbc800000, v134
	v_mul_f32_e32 v175, v175, v175
	v_mul_f32_e32 v173, v173, v173
	v_fmac_f32_e32 v175, v174, v174
	v_fmac_f32_e32 v173, v172, v172
	v_fmamk_f32 v174, v171, 0xbc800000, v85
	v_fmamk_f32 v176, v171, 0xbc800000, v83
	v_add_f32_e32 v172, v175, v173
	v_fmamk_f32 v173, v171, 0xbc800000, v84
	v_fmamk_f32 v175, v171, 0xbc800000, v82
	v_mul_f32_e32 v176, v176, v176
	v_mul_f32_e32 v174, v174, v174
	v_fmac_f32_e32 v176, v175, v175
	v_fmac_f32_e32 v174, v173, v173
	v_add_f32_e32 v173, v176, v174
	v_fmamk_f32 v174, v171, 0xbc800000, v65
	v_fmamk_f32 v176, v171, 0xbc800000, v63
	v_add_f32_e32 v172, v172, v173
	v_fmamk_f32 v173, v171, 0xbc800000, v64
	v_fmamk_f32 v175, v171, 0xbc800000, v62
	v_mul_f32_e32 v176, v176, v176
	v_mul_f32_e32 v174, v174, v174
	v_fmac_f32_e32 v176, v175, v175
	v_fmac_f32_e32 v174, v173, v173
	v_add_f32_e32 v173, v176, v174
	v_fmamk_f32 v174, v171, 0xbc800000, v61
	v_fmamk_f32 v176, v171, 0xbc800000, v59
	v_add_f32_e32 v172, v173, v172
	v_fmamk_f32 v173, v171, 0xbc800000, v60
	v_fmamk_f32 v175, v171, 0xbc800000, v58
	v_mul_f32_e32 v176, v176, v176
	v_mul_f32_e32 v174, v174, v174
	v_fmac_f32_e32 v176, v175, v175
	v_fmac_f32_e32 v174, v173, v173
	v_add_f32_e32 v173, v176, v174
	v_add_f32_e32 v172, v173, v172
	v_mov_b32_e32 v167, v172
	s_nop 1
	v_permlane16_swap_b32 v167, v172
	s_waitcnt lgkmcnt(0)
	v_add_f32_e32 v167, v172, v167
	v_mov_b32_e32 v169, v167
	s_nop 1
	v_permlane32_swap_b32 v169, v167
	s_and_saveexec_b64 s[0:1], vcc
	s_cbranch_execz .LBB0_835
	v_mul_f32_e32 v172, 0x3c800000, v171
	s_waitcnt lgkmcnt(0)
	v_add_f32_e32 v173, v167, v169
	ds_write_b64 v170, v[172:173] offset:5632
